# k53: k52 + staged lgkmcnt waits in front of the second-half PV MFMAs of every attention tile body (MFMA/LDS interleave)
# baseline (speedup 1.0000x reference)
; #define LAS __attribute__((address_space(3)))
; template <bool BAND>
; __device__ __forceinline__ void tile_body(f32x16* o, float& l_reg, const bf16x8* qr, const LAS unsigned char* kbs, const LAS float* wb, int vb, float ci, int hi, int keybase, int qabs) {
;     f32x16 p0, p1;
; #pragma unroll
;     for (int g4 = 0; g4 < 4; ++g4) {
;         const f32x4 ba = *(const LAS f32x4*)(wb + 8 * g4 + 4 * hi) + ci, bb = *(const LAS f32x4*)(wb + 32 + 8 * g4 + 4 * hi) + ci;
; #pragma unroll
;         for (int e = 0; e < 4; ++e) { p0[4 * g4 + e] = ba[e]; p1[4 * g4 + e] = bb[e]; }
;     }
; #pragma unroll
;     for (int d0 = 0; d0 < 4; ++d0) {
;         const bf16x8 b0 = *(const LAS bf16x8*)(kbs + d0 * 2048), b1 = *(const LAS bf16x8*)(kbs + d0 * 2048 + 512);
;         p0 = __builtin_amdgcn_mfma_f32_32x32x16_bf16(b0, qr[d0], p0, 0, 0, 0); p1 = __builtin_amdgcn_mfma_f32_32x32x16_bf16(b1, qr[d0], p1, 0, 0, 0); }
.LBB0_777:
	s_waitcnt lgkmcnt(0)
	s_barrier
	s_waitcnt vmcnt(8)
	s_nop 1
	v_add_f32_dpp v0, v140, v140 row_shl:1 row_mask:0xf bank_mask:0xf bound_ctrl:1
	s_nop 1
	v_add_f32_dpp v0, v0, v0 row_shl:2 row_mask:0xf bank_mask:0xf bound_ctrl:1
	s_nop 1
	v_add_f32_dpp v0, v0, v0 row_shl:4 row_mask:0xf bank_mask:0xf bound_ctrl:1
	s_nop 1
	v_add_f32_dpp v0, v0, v0 row_shl:8 row_mask:0xf bank_mask:0xf bound_ctrl:1
	s_nop 0
	v_readlane_b32 s28, v0, 16
	v_readlane_b32 s67, v0, 32
	v_readlane_b32 s66, v0, 48
	s_nop 0
	v_mul_f32_e32 v149, s67, v192
	v_fmac_f32_e32 v149, s28, v191
	v_fmac_f32_e32 v149, s66, v193
	v_add_f32_e32 v149, v0, v149
	s_xor_b32 s74, s70, 1
	v_add_f32_e32 v0, v150, v149
	s_lshl_b32 s12, s74, 8
	v_sub_f32_e32 v0, v0, v140
	s_add_i32 s71, s53, s12
	s_lshl_b32 s78, s74, 14
	s_max_i32 s12, s48, 4
	v_mul_f32_e32 v140, 0x3fb8aa3b, v0
	v_lshl_add_u32 v0, v137, 2, s71
	v_readfirstlane_b32 s76, v149
	v_add_u32_e32 v149, s78, v143
	s_add_i32 s28, s12, -4
	ds_write_b32 v0, v140 offset:32768
	s_waitcnt vmcnt(4)
	ds_write_b128 v149, v[66:69]
	ds_write_b128 v149, v[74:77] offset:8192
	s_lshl_b64 s[12:13], s[28:29], 11
	s_waitcnt lgkmcnt(0)
	v_lshl_add_u64 v[66:67], v[110:111], 0, s[12:13]
	s_lshl_b64 s[12:13], s[28:29], 16
	global_load_dword v140, v[66:67], off
	v_lshl_add_u64 v[74:75], v[106:107], 0, s[12:13]
	global_load_dwordx4 v[66:69], v[74:75], off
	s_nop 0
	v_lshl_add_u64 v[152:153], v[108:109], 0, s[12:13]
	s_not_b64 s[12:13], s[58:59]
	global_load_dwordx4 v[74:77], v[152:153], off
	s_andn2_b64 vcc, exec, s[58:59]
	s_cbranch_vccnz .LBB0_792
	s_and_b64 vcc, exec, s[98:99]
	s_cbranch_vccnz .LBB0_792
	s_sub_i32 s28, s75, 64
	s_cmp_gt_i32 s28, s73
	s_cbranch_scc1 .LBB0_792
	s_lshl_b32 s64, s70, 8
	s_lshl_b32 s28, s70, 14
	s_add_i32 s66, s53, s64
	s_cmp_lt_i32 s48, s72
	v_add_u32_e32 v151, s28, v144
	s_mov_b64 s[64:65], -1
	v_add_u32_e32 v152, s28, v145
	v_lshl_add_u32 v153, v142, 2, s66
	s_cbranch_scc1 .LBB0_789
	ds_read_b128 v[34:37], v153 offset:32768
	ds_read_b128 v[38:41], v153 offset:32800
	ds_read_b128 v[42:45], v153 offset:32832
	ds_read_b128 v[46:49], v153 offset:32864
	ds_read_b128 v[50:53], v153 offset:32896
	ds_read_b128 v[54:57], v153 offset:32928
	ds_read_b128 v[58:61], v153 offset:32960
	ds_read_b128 v[62:65], v153 offset:32992
	ds_read_b128 v[154:157], v152
	ds_read_b128 v[158:161], v152 offset:512
	s_waitcnt lgkmcnt(4)
	ds_read_b128 v[210:213], v152 offset:2048
	ds_read_b128 v[214:217], v152 offset:2560
	ds_read_b128 v[218:221], v152 offset:4096
	ds_read_b128 v[222:225], v152 offset:4608
	ds_read_b128 v[226:229], v152 offset:6656
	ds_read_b128 v[230:233], v152 offset:6144
	v_pk_add_f32 v[56:57], v[118:119], v[56:57]
	s_waitcnt lgkmcnt(9)
	v_pk_add_f32 v[60:61], v[122:123], v[60:61]
	s_waitcnt lgkmcnt(8)
	v_pk_add_f32 v[64:65], v[126:127], v[64:65]
	v_pk_add_f32 v[52:53], v[114:115], v[52:53]
	v_pk_add_f32 v[62:63], v[124:125], v[62:63]
	v_pk_add_f32 v[58:59], v[120:121], v[58:59]
	v_pk_add_f32 v[54:55], v[116:117], v[54:55]
	v_pk_add_f32 v[50:51], v[112:113], v[50:51]
	v_pk_add_f32 v[48:49], v[126:127], v[48:49]
	v_pk_add_f32 v[44:45], v[122:123], v[44:45]
	v_pk_add_f32 v[40:41], v[118:119], v[40:41]
	v_pk_add_f32 v[36:37], v[114:115], v[36:37]
	v_pk_add_f32 v[46:47], v[124:125], v[46:47]
	v_pk_add_f32 v[42:43], v[120:121], v[42:43]
	v_pk_add_f32 v[38:39], v[116:117], v[38:39]
	v_pk_add_f32 v[34:35], v[112:113], v[34:35]
	s_waitcnt lgkmcnt(6)
	v_mfma_f32_32x32x16_bf16 v[50:65], v[158:161], v[94:97], v[50:65]
	v_mfma_f32_32x32x16_bf16 v[34:49], v[154:157], v[94:97], v[34:49]
	s_waitcnt lgkmcnt(4)
	v_mfma_f32_32x32x16_bf16 v[50:65], v[214:217], v[98:101], v[50:65]
	v_mfma_f32_32x32x16_bf16 v[34:49], v[210:213], v[98:101], v[34:49]
	s_waitcnt lgkmcnt(2)
	v_mfma_f32_32x32x16_bf16 v[50:65], v[222:225], v[102:105], v[50:65]
	v_mfma_f32_32x32x16_bf16 v[34:49], v[218:221], v[102:105], v[34:49]
	s_waitcnt lgkmcnt(1)
	v_mfma_f32_32x32x16_bf16 v[50:65], v[226:229], v[90:93], v[50:65]
	v_add_u32_e32 v154, s75, v142
	v_subrev_u32_e32 v156, 32, v154
	v_subrev_u32_e32 v155, 64, v154
	v_cmp_le_i32_e32 vcc, v156, v147
	s_waitcnt lgkmcnt(0)
	v_mfma_f32_32x32x16_bf16 v[34:49], v[230:233], v[90:93], v[34:49]
	s_nop 5
	v_cndmask_b32_e32 v50, v134, v50, vcc
	v_cmp_lt_i32_e32 vcc, v155, v147
	s_nop 3
	v_cndmask_b32_e32 v35, v134, v35, vcc
	v_cmp_le_i32_e32 vcc, v155, v147
	v_subrev_u32_e32 v155, 31, v154
	v_exp_f32_e32 v35, v35
	v_cndmask_b32_e32 v34, v134, v34, vcc
	v_cmp_le_i32_e32 vcc, v155, v147
	v_subrev_u32_e32 v155, 62, v154
	v_exp_f32_e32 v34, v34
	v_cndmask_b32_e32 v51, v134, v51, vcc
	v_cmp_le_i32_e32 vcc, v155, v147
	s_nop 1
	v_cndmask_b32_e32 v155, v134, v36, vcc
	v_subrev_u32_e32 v36, 30, v154
	v_cmp_le_i32_e32 vcc, v36, v147
	v_subrev_u32_e32 v36, 61, v154
	s_nop 0
	v_cndmask_b32_e32 v52, v134, v52, vcc
	v_cmp_le_i32_e32 vcc, v36, v147
	v_subrev_u32_e32 v36, 29, v154
	s_nop 0
	v_cndmask_b32_e32 v156, v134, v37, vcc
	v_cmp_le_i32_e32 vcc, v36, v147
	v_subrev_u32_e32 v36, 56, v154
	v_exp_f32_e32 v37, v51
	v_cndmask_b32_e32 v53, v134, v53, vcc
	v_cmp_le_i32_e32 vcc, v36, v147
	v_subrev_u32_e32 v36, 24, v154
	s_nop 0
	v_cndmask_b32_e32 v157, v134, v38, vcc
	v_cmp_le_i32_e32 vcc, v36, v147
	v_subrev_u32_e32 v36, 55, v154
	v_exp_f32_e32 v38, v155
	v_cndmask_b32_e32 v54, v134, v54, vcc
	v_cmp_le_i32_e32 vcc, v36, v147
	v_subrev_u32_e32 v36, 23, v154
	s_nop 0
	v_cndmask_b32_e32 v158, v134, v39, vcc
	v_cmp_le_i32_e32 vcc, v36, v147
	v_subrev_u32_e32 v36, 54, v154
	v_exp_f32_e32 v39, v156
	v_cndmask_b32_e32 v55, v134, v55, vcc
	v_cmp_le_i32_e32 vcc, v36, v147
	v_subrev_u32_e32 v36, 22, v154
	v_cvt_pk_bf16_f32 v156, v34, v35
; __device__ __forceinline__ void pv(f32x16* o, int vb, bf16x8 pa0, bf16x8 pa1, bf16x8 pa2, bf16x8 pa3) {
; #pragma unroll
;     for (int d0 = 0; d0 < 2; ++d0) { s16x4 lo[4], hi[4];
; #pragma unroll
;         for (int ks = 0; ks < 4; ++ks) {
;             asm volatile("ds_read_b64_tr_b16 %0,%1 offset:%c2" : "=&v"(lo[ks]) : "v"(vb), "i"(d0 * 4096 + ks * 1024) : "memory");
;             asm volatile("ds_read_b64_tr_b16 %0,%1 offset:%c2" : "=&v"(hi[ks]) : "v"(vb), "i"(d0 * 4096 + ks * 1024 + 512) : "memory"); }
;         asm volatile("s_waitcnt lgkmcnt(0)" ::: "memory"); __builtin_amdgcn_sched_barrier(0);
;     ...
;         o[d0] = __builtin_amdgcn_mfma_f32_32x32x16_bf16(pa0, PK(0), o[d0], 0, 0, 0);
;         o[d0] = __builtin_amdgcn_mfma_f32_32x32x16_bf16(pa1, PK(1), o[d0], 0, 0, 0);
;         o[d0] = __builtin_amdgcn_mfma_f32_32x32x16_bf16(pa2, PK(2), o[d0], 0, 0, 0);
;         o[d0] = __builtin_amdgcn_mfma_f32_32x32x16_bf16(pa3, PK(3), o[d0], 0, 0, 0);
;     ...
;     }
; template <bool BAND>
; __device__ __forceinline__ void tile_body(f32x16* o, float& l_reg, const bf16x8* qr, const LAS unsigned char* kbs, const LAS float* wb, int vb, float ci, int hi, int keybase, int qabs) {
;     ...
;     if (BAND) {
; #pragma unroll
;         for (int r = 0; r < 16; ++r) { const int key = keybase + 8 * (r >> 2) + (r & 3); if (key > qabs) p0[r] = -INFINITY; if (key + 32 > qabs) p1[r] = -INFINITY; }
;     }
;     f32x2 s2 = {0.f, 0.f};
; #pragma unroll
;     for (int r = 0; r < 16; r += 2) {
;         p0[r] = __builtin_amdgcn_exp2f(p0[r]); p0[r + 1] = __builtin_amdgcn_exp2f(p0[r + 1]); p1[r] = __builtin_amdgcn_exp2f(p1[r]); p1[r + 1] = __builtin_amdgcn_exp2f(p1[r + 1]);
;         s2 += (f32x2){p0[r], p0[r + 1]}; s2 += (f32x2){p1[r], p1[r + 1]}; }
;     l_reg += s2.x + s2.y;
;     u32x4 pw0, pw1, pw2, pw3;
;     pw0 = (u32x4){cvtpk(p0[0], p0[1]), cvtpk(p0[2], p0[3]), cvtpk(p0[4], p0[5]), cvtpk(p0[6], p0[7])};
;     pw1 = (u32x4){cvtpk(p0[8], p0[9]), cvtpk(p0[10], p0[11]), cvtpk(p0[12], p0[13]), cvtpk(p0[14], p0[15])};
;     pw2 = (u32x4){cvtpk(p1[0], p1[1]), cvtpk(p1[2], p1[3]), cvtpk(p1[4], p1[5]), cvtpk(p1[6], p1[7])};
;     pw3 = (u32x4){cvtpk(p1[8], p1[9]), cvtpk(p1[10], p1[11]), cvtpk(p1[12], p1[13]), cvtpk(p1[14], p1[15])};
;     pv(o, vb, __builtin_bit_cast(bf16x8, pw0), __builtin_bit_cast(bf16x8, pw1), __builtin_bit_cast(bf16x8, pw2), __builtin_bit_cast(bf16x8, pw3));
	v_cndmask_b32_e32 v159, v134, v40, vcc
	v_cmp_le_i32_e32 vcc, v36, v147
	v_subrev_u32_e32 v36, 53, v154
	v_exp_f32_e32 v40, v52
	v_cndmask_b32_e32 v56, v134, v56, vcc
	v_cmp_le_i32_e32 vcc, v36, v147
	v_subrev_u32_e32 v36, 21, v154
	s_nop 0
	v_cndmask_b32_e32 v160, v134, v41, vcc
	v_cmp_le_i32_e32 vcc, v36, v147
	v_subrev_u32_e32 v36, 48, v154
	v_exp_f32_e32 v41, v53
	v_cndmask_b32_e32 v57, v134, v57, vcc
	v_cmp_le_i32_e32 vcc, v36, v147
	v_add_u32_e32 v36, -16, v154
	v_exp_f32_e32 v51, v57
	v_cndmask_b32_e32 v161, v134, v42, vcc
	v_cmp_le_i32_e32 vcc, v36, v147
	v_subrev_u32_e32 v36, 47, v154
	v_exp_f32_e32 v52, v161
	v_cndmask_b32_e32 v58, v134, v58, vcc
	v_cmp_le_i32_e32 vcc, v36, v147
	v_add_u32_e32 v36, -15, v154
	s_nop 0
	v_cndmask_b32_e32 v162, v134, v43, vcc
	v_cmp_le_i32_e32 vcc, v36, v147
	v_subrev_u32_e32 v36, 46, v154
	v_pk_add_f32 v[42:43], v[34:35], 0 op_sel_hi:[1,0]
	v_cndmask_b32_e32 v59, v134, v59, vcc
	v_cmp_le_i32_e32 vcc, v36, v147
	v_add_u32_e32 v36, -14, v154
	v_exp_f32_e32 v53, v162
	v_cndmask_b32_e32 v163, v134, v44, vcc
	v_cmp_le_i32_e32 vcc, v36, v147
	v_subrev_u32_e32 v36, 45, v154
	v_exp_f32_e32 v44, v157
	v_cndmask_b32_e32 v60, v134, v60, vcc
	v_cmp_le_i32_e32 vcc, v36, v147
	v_add_u32_e32 v36, -13, v154
	v_cvt_pk_bf16_f32 v157, v38, v39
	v_cndmask_b32_e32 v164, v134, v45, vcc
	v_cmp_le_i32_e32 vcc, v36, v147
	v_subrev_u32_e32 v36, 40, v154
	v_exp_f32_e32 v45, v158
	v_cndmask_b32_e32 v61, v134, v61, vcc
	v_cmp_le_i32_e32 vcc, v36, v147
	v_add_u32_e32 v36, -8, v154
	v_exp_f32_e32 v57, v164
	v_cndmask_b32_e32 v165, v134, v46, vcc
	v_cmp_le_i32_e32 vcc, v36, v147
	v_subrev_u32_e32 v36, 39, v154
	v_exp_f32_e32 v46, v54
	v_cndmask_b32_e32 v62, v134, v62, vcc
	v_cmp_le_i32_e32 vcc, v36, v147
	v_add_u32_e32 v36, -7, v154
	v_exp_f32_e32 v54, v58
	v_cndmask_b32_e32 v166, v134, v47, vcc
	v_cmp_le_i32_e32 vcc, v36, v147
	v_subrev_u32_e32 v36, 38, v154
	v_exp_f32_e32 v47, v55
	v_cndmask_b32_e32 v63, v134, v63, vcc
	v_cmp_le_i32_e32 vcc, v36, v147
	v_add_u32_e32 v36, -6, v154
	v_exp_f32_e32 v55, v59
	v_cndmask_b32_e32 v167, v134, v48, vcc
	v_cmp_le_i32_e32 vcc, v36, v147
	v_subrev_u32_e32 v36, 37, v154
	v_exp_f32_e32 v48, v159
	v_cndmask_b32_e32 v168, v134, v64, vcc
	v_cmp_le_i32_e32 vcc, v36, v147
	v_add_u32_e32 v36, -5, v154
	v_exp_f32_e32 v58, v60
	v_cndmask_b32_e32 v169, v134, v49, vcc
	v_cmp_le_i32_e32 vcc, v36, v147
	v_exp_f32_e32 v36, v50
	v_exp_f32_e32 v49, v160
	v_exp_f32_e32 v50, v56
	v_exp_f32_e32 v56, v163
	v_pk_add_f32 v[42:43], v[36:37], v[42:43]
	v_exp_f32_e32 v59, v61
	v_pk_add_f32 v[42:43], v[38:39], v[42:43]
	v_exp_f32_e32 v64, v167
	v_pk_add_f32 v[42:43], v[40:41], v[42:43]
	v_cvt_pk_bf16_f32 v167, v50, v51
	v_pk_add_f32 v[42:43], v[44:45], v[42:43]
	v_exp_f32_e32 v60, v165
	v_pk_add_f32 v[42:43], v[46:47], v[42:43]
	v_exp_f32_e32 v61, v166
	v_pk_add_f32 v[42:43], v[48:49], v[42:43]
	v_cvt_pk_bf16_f32 v160, v52, v53
	v_pk_add_f32 v[42:43], v[50:51], v[42:43]
	ds_read_b64_tr_b16 v[50:51],v151 offset:0
	v_exp_f32_e32 v62, v62
	v_pk_add_f32 v[42:43], v[52:53], v[42:43]
	ds_read_b64_tr_b16 v[52:53],v151 offset:512
	v_exp_f32_e32 v63, v63
	v_pk_add_f32 v[42:43], v[54:55], v[42:43]
	v_exp_f32_e32 v172, v168
	v_cvt_pk_bf16_f32 v168, v54, v55
	ds_read_b64_tr_b16 v[54:55],v151 offset:1024
	v_cndmask_b32_e32 v154, v134, v65, vcc
	v_pk_add_f32 v[42:43], v[56:57], v[42:43]
	v_exp_f32_e32 v65, v169
	v_cvt_pk_bf16_f32 v161, v56, v57
	ds_read_b64_tr_b16 v[56:57],v151 offset:1536
	v_pk_add_f32 v[42:43], v[58:59], v[42:43]
	v_exp_f32_e32 v173, v154
	v_cvt_pk_bf16_f32 v169, v58, v59
	ds_read_b64_tr_b16 v[58:59],v151 offset:2048
	v_pk_add_f32 v[42:43], v[60:61], v[42:43]
	v_cvt_pk_bf16_f32 v162, v60, v61
	ds_read_b64_tr_b16 v[60:61],v151 offset:2560
	v_pk_add_f32 v[42:43], v[62:63], v[42:43]
	v_cvt_pk_bf16_f32 v170, v62, v63
	ds_read_b64_tr_b16 v[62:63],v151 offset:3072
	v_pk_add_f32 v[42:43], v[64:65], v[42:43]
	v_cvt_pk_bf16_f32 v163, v64, v65
	ds_read_b64_tr_b16 v[64:65],v151 offset:3584
	v_pk_add_f32 v[42:43], v[172:173], v[42:43]
	s_waitcnt lgkmcnt(0)
	v_cvt_pk_bf16_f32 v158, v44, v45
	v_add_f32_e32 v42, v42, v43
	v_add_f32_e32 v154, v148, v42
	v_cvt_pk_bf16_f32 v159, v48, v49
	v_cvt_pk_bf16_f32 v164, v36, v37
	v_cvt_pk_bf16_f32 v165, v40, v41
	v_cvt_pk_bf16_f32 v166, v46, v47
	v_cvt_pk_bf16_f32 v171, v172, v173
	v_mfma_f32_32x32x16_bf16 v[2:17], v[156:159], v[50:53], v[2:17]
	ds_read_b64_tr_b16 v[172:173],v151 offset:4096
	ds_read_b64_tr_b16 v[174:175],v151 offset:4608
	ds_read_b64_tr_b16 v[176:177],v151 offset:5120
	ds_read_b64_tr_b16 v[178:179],v151 offset:5632
	ds_read_b64_tr_b16 v[180:181],v151 offset:6144
	ds_read_b64_tr_b16 v[182:183],v151 offset:6656
	ds_read_b64_tr_b16 v[184:185],v151 offset:7168
	v_mfma_f32_32x32x16_bf16 v[2:17], v[160:163], v[54:57], v[2:17]
	ds_read_b64_tr_b16 v[186:187],v151 offset:7680
	s_nop 0
	v_mfma_f32_32x32x16_bf16 v[2:17], v[164:167], v[58:61], v[2:17]
	v_mfma_f32_32x32x16_bf16 v[2:17], v[168:171], v[62:65], v[2:17]
	s_waitcnt lgkmcnt(6)
	v_mfma_f32_32x32x16_bf16 v[18:33], v[156:159], v[172:175], v[18:33]
	s_mov_b64 s[64:65], 0
	s_waitcnt lgkmcnt(4)
	v_mfma_f32_32x32x16_bf16 v[18:33], v[160:163], v[176:179], v[18:33]
	s_waitcnt lgkmcnt(2)
	v_mfma_f32_32x32x16_bf16 v[18:33], v[164:167], v[180:183], v[18:33]
	s_waitcnt lgkmcnt(0)
	v_mfma_f32_32x32x16_bf16 v[18:33], v[168:171], v[184:187], v[18:33]
; #define LAS __attribute__((address_space(3)))
; __device__ __forceinline__ unsigned cvtpk(float lo, float hi) { typedef __bf16 bf16x2_t __attribute__((ext_vector_type(2))); f32x2 v = {lo, hi}; bf16x2_t b = __builtin_convertvector(v, bf16x2_t); return __builtin_bit_cast(unsigned, b); }
; template <bool BAND>
; __device__ __forceinline__ void tile_body(f32x16* o, float& l_reg, const bf16x8* qr, const LAS unsigned char* kbs, const LAS float* wb, int vb, float ci, int hi, int keybase, int qabs) {
;     f32x16 p0, p1;
; #pragma unroll
;     for (int g4 = 0; g4 < 4; ++g4) {
;         const f32x4 ba = *(const LAS f32x4*)(wb + 8 * g4 + 4 * hi) + ci, bb = *(const LAS f32x4*)(wb + 32 + 8 * g4 + 4 * hi) + ci;
; #pragma unroll
;         for (int e = 0; e < 4; ++e) { p0[4 * g4 + e] = ba[e]; p1[4 * g4 + e] = bb[e]; }
;     }
; #pragma unroll
;     for (int d0 = 0; d0 < 4; ++d0) {
;         const bf16x8 b0 = *(const LAS bf16x8*)(kbs + d0 * 2048), b1 = *(const LAS bf16x8*)(kbs + d0 * 2048 + 512);
;         p0 = __builtin_amdgcn_mfma_f32_32x32x16_bf16(b0, qr[d0], p0, 0, 0, 0); p1 = __builtin_amdgcn_mfma_f32_32x32x16_bf16(b1, qr[d0], p1, 0, 0, 0); }
;     if (BAND) {
; #pragma unroll
;         for (int r = 0; r < 16; ++r) { const int key = keybase + 8 * (r >> 2) + (r & 3); if (key > qabs) p0[r] = -INFINITY; if (key + 32 > qabs) p1[r] = -INFINITY; }
;     }
;     f32x2 s2 = {0.f, 0.f};
; #pragma unroll
;     for (int r = 0; r < 16; r += 2) {
;         p0[r] = __builtin_amdgcn_exp2f(p0[r]); p0[r + 1] = __builtin_amdgcn_exp2f(p0[r + 1]); p1[r] = __builtin_amdgcn_exp2f(p1[r]); p1[r + 1] = __builtin_amdgcn_exp2f(p1[r + 1]);
;         s2 += (f32x2){p0[r], p0[r + 1]}; s2 += (f32x2){p1[r], p1[r + 1]}; }
;     l_reg += s2.x + s2.y;
;     u32x4 pw0, pw1, pw2, pw3;
;     pw0 = (u32x4){cvtpk(p0[0], p0[1]), cvtpk(p0[2], p0[3]), cvtpk(p0[4], p0[5]), cvtpk(p0[6], p0[7])};
;     pw1 = (u32x4){cvtpk(p0[8], p0[9]), cvtpk(p0[10], p0[11]), cvtpk(p0[12], p0[13]), cvtpk(p0[14], p0[15])};
;     pw2 = (u32x4){cvtpk(p1[0], p1[1]), cvtpk(p1[2], p1[3]), cvtpk(p1[4], p1[5]), cvtpk(p1[6], p1[7])};
;     pw3 = (u32x4){cvtpk(p1[8], p1[9]), cvtpk(p1[10], p1[11]), cvtpk(p1[12], p1[13]), cvtpk(p1[14], p1[15])};
;     pv(o, vb, __builtin_bit_cast(bf16x8, pw0), __builtin_bit_cast(bf16x8, pw1), __builtin_bit_cast(bf16x8, pw2), __builtin_bit_cast(bf16x8, pw3));
.LBB0_789:
	s_andn2_b64 vcc, exec, s[64:65]
	s_cbranch_vccnz .Lmy_attjoin_A
	s_nop 4
	ds_read_b128 v[34:37], v153 offset:32768
	ds_read_b128 v[38:41], v153 offset:32800
	ds_read_b128 v[42:45], v153 offset:32832
	ds_read_b128 v[46:49], v153 offset:32864
	s_nop 0
	ds_read_b128 v[50:53], v153 offset:32896
	ds_read_b128 v[54:57], v153 offset:32928
	ds_read_b128 v[58:61], v153 offset:32960
	ds_read_b128 v[62:65], v153 offset:32992
	ds_read_b128 v[154:157], v152
	ds_read_b128 v[158:161], v152 offset:512
	s_waitcnt lgkmcnt(6)
	ds_read_b128 v[210:213], v152 offset:2048
	ds_read_b128 v[214:217], v152 offset:2560
	ds_read_b128 v[218:221], v152 offset:4096
	ds_read_b128 v[222:225], v152 offset:4608
	ds_read_b128 v[226:229], v152 offset:6144
	ds_read_b128 v[230:233], v152 offset:6656
	v_pk_add_f32 v[48:49], v[126:127], v[48:49]
	v_pk_add_f32 v[44:45], v[122:123], v[44:45]
	v_pk_add_f32 v[40:41], v[118:119], v[40:41]
	v_pk_add_f32 v[36:37], v[114:115], v[36:37]
	v_pk_add_f32 v[46:47], v[124:125], v[46:47]
	v_pk_add_f32 v[42:43], v[120:121], v[42:43]
	v_pk_add_f32 v[38:39], v[116:117], v[38:39]
	v_pk_add_f32 v[34:35], v[112:113], v[34:35]
	s_waitcnt lgkmcnt(8)
	v_pk_add_f32 v[64:65], v[126:127], v[64:65]
	v_pk_add_f32 v[60:61], v[122:123], v[60:61]
	s_waitcnt lgkmcnt(7)
	v_mfma_f32_32x32x16_bf16 v[34:49], v[154:157], v[94:97], v[34:49]
	v_add_f32_e64 v56, v118, v56
	v_add_f32_e64 v57, v119, v57
	v_add_f32_e64 v52, v114, v52
	v_add_f32_e64 v53, v115, v53
	v_add_f32_e64 v62, v124, v62
	v_add_f32_e64 v63, v125, v63
	v_pk_add_f32 v[58:59], v[120:121], v[58:59]
	v_pk_add_f32 v[54:55], v[116:117], v[54:55]
	v_pk_add_f32 v[50:51], v[112:113], v[50:51]
	s_waitcnt lgkmcnt(6)
	s_nop 0
	v_mfma_f32_32x32x16_bf16 v[50:65], v[158:161], v[94:97], v[50:65]
	s_waitcnt lgkmcnt(5)
	v_mfma_f32_32x32x16_bf16 v[34:49], v[210:213], v[98:101], v[34:49]
	s_waitcnt lgkmcnt(4)
	v_mfma_f32_32x32x16_bf16 v[50:65], v[214:217], v[98:101], v[50:65]
	s_waitcnt lgkmcnt(3)
	v_mfma_f32_32x32x16_bf16 v[34:49], v[218:221], v[102:105], v[34:49]
	s_waitcnt lgkmcnt(2)
	v_mfma_f32_32x32x16_bf16 v[50:65], v[222:225], v[102:105], v[50:65]
	s_waitcnt lgkmcnt(1)
	v_mfma_f32_32x32x16_bf16 v[34:49], v[226:229], v[90:93], v[34:49]
	s_waitcnt lgkmcnt(0)
	v_mfma_f32_32x32x16_bf16 v[50:65], v[230:233], v[90:93], v[50:65]
	s_nop 9
	v_exp_f32_e32 v34, v34
	v_exp_f32_e32 v35, v35
	v_exp_f32_e32 v36, v36
	v_exp_f32_e32 v37, v37
	v_exp_f32_e32 v38, v38
	v_pk_add_f32 v[152:153], v[34:35], 0 op_sel_hi:[1,0]
	v_exp_f32_e32 v39, v39
	v_exp_f32_e32 v50, v50
	v_exp_f32_e32 v51, v51
	v_exp_f32_e32 v52, v52
	v_exp_f32_e32 v53, v53
	v_exp_f32_e32 v54, v54
	v_pk_add_f32 v[152:153], v[50:51], v[152:153]
	v_exp_f32_e32 v55, v55
	v_pk_add_f32 v[152:153], v[36:37], v[152:153]
	v_exp_f32_e32 v40, v40
	v_exp_f32_e32 v41, v41
	v_pk_add_f32 v[152:153], v[52:53], v[152:153]
	v_exp_f32_e32 v56, v56
	v_exp_f32_e32 v57, v57
	v_pk_add_f32 v[152:153], v[38:39], v[152:153]
	v_exp_f32_e32 v42, v42
	v_exp_f32_e32 v43, v43
	v_pk_add_f32 v[152:153], v[54:55], v[152:153]
	v_exp_f32_e32 v58, v58
	v_exp_f32_e32 v59, v59
	v_pk_add_f32 v[152:153], v[40:41], v[152:153]
	v_exp_f32_e32 v44, v44
	v_exp_f32_e32 v45, v45
	v_pk_add_f32 v[152:153], v[56:57], v[152:153]
	v_exp_f32_e32 v60, v60
	v_exp_f32_e32 v61, v61
	v_pk_add_f32 v[152:153], v[42:43], v[152:153]
	v_exp_f32_e32 v46, v46
	v_exp_f32_e32 v47, v47
	v_cvt_pk_bf16_f32 v34, v34, v35
	v_cvt_pk_bf16_f32 v35, v36, v37
	v_cvt_pk_bf16_f32 v36, v38, v39
	v_cvt_pk_bf16_f32 v38, v42, v43
	v_cvt_pk_bf16_f32 v42, v50, v51
	ds_read_b64_tr_b16 v[50:51],v151 offset:0
	v_pk_add_f32 v[152:153], v[58:59], v[152:153]
	v_exp_f32_e32 v62, v62
	v_exp_f32_e32 v63, v63
	v_cvt_pk_bf16_f32 v43, v52, v53
	ds_read_b64_tr_b16 v[52:53],v151 offset:512
	v_pk_add_f32 v[152:153], v[44:45], v[152:153]
	v_exp_f32_e32 v48, v48
	v_exp_f32_e32 v49, v49
	v_cvt_pk_bf16_f32 v39, v44, v45
	v_cvt_pk_bf16_f32 v44, v54, v55
	ds_read_b64_tr_b16 v[54:55],v151 offset:1024
	v_pk_add_f32 v[152:153], v[60:61], v[152:153]
	v_exp_f32_e32 v64, v64
	v_exp_f32_e32 v65, v65
	v_cvt_pk_bf16_f32 v45, v56, v57
	ds_read_b64_tr_b16 v[56:57],v151 offset:1536
	v_pk_add_f32 v[152:153], v[46:47], v[152:153]
	v_cvt_pk_bf16_f32 v37, v40, v41
	v_cvt_pk_bf16_f32 v40, v46, v47
	v_cvt_pk_bf16_f32 v46, v58, v59
	ds_read_b64_tr_b16 v[58:59],v151 offset:2048
	v_pk_add_f32 v[152:153], v[62:63], v[152:153]
	v_cvt_pk_bf16_f32 v47, v60, v61
	ds_read_b64_tr_b16 v[60:61],v151 offset:2560
	v_pk_add_f32 v[152:153], v[48:49], v[152:153]
	v_cvt_pk_bf16_f32 v41, v48, v49
	v_cvt_pk_bf16_f32 v48, v62, v63
	ds_read_b64_tr_b16 v[62:63],v151 offset:3072
	v_pk_add_f32 v[152:153], v[64:65], v[152:153]
	v_cvt_pk_bf16_f32 v49, v64, v65
	ds_read_b64_tr_b16 v[64:65],v151 offset:3584
	s_waitcnt lgkmcnt(0)
	v_add_f32_e32 v152, v152, v153
	v_add_f32_e32 v154, v148, v152
	v_mfma_f32_32x32x16_bf16 v[2:17], v[34:37], v[50:53], v[2:17]
	ds_read_b64_tr_b16 v[50:51],v151 offset:4096
	ds_read_b64_tr_b16 v[52:53],v151 offset:4608
	v_mfma_f32_32x32x16_bf16 v[2:17], v[38:41], v[54:57], v[2:17]
	ds_read_b64_tr_b16 v[54:55],v151 offset:5120
	ds_read_b64_tr_b16 v[56:57],v151 offset:5632
	v_mfma_f32_32x32x16_bf16 v[2:17], v[42:45], v[58:61], v[2:17]
	ds_read_b64_tr_b16 v[58:59],v151 offset:6144
	ds_read_b64_tr_b16 v[60:61],v151 offset:6656
	ds_read_b64_tr_b16 v[156:157],v151 offset:7168
	ds_read_b64_tr_b16 v[158:159],v151 offset:7680
	s_nop 0
	v_mfma_f32_32x32x16_bf16 v[2:17], v[46:49], v[62:65], v[2:17]
	s_waitcnt lgkmcnt(6)
	v_mfma_f32_32x32x16_bf16 v[18:33], v[34:37], v[50:53], v[18:33]
	s_waitcnt lgkmcnt(4)
	v_mfma_f32_32x32x16_bf16 v[18:33], v[38:41], v[54:57], v[18:33]
	s_waitcnt lgkmcnt(2)
	v_mfma_f32_32x32x16_bf16 v[18:33], v[42:45], v[58:61], v[18:33]
	s_waitcnt lgkmcnt(0)
	v_mfma_f32_32x32x16_bf16 v[18:33], v[46:49], v[156:159], v[18:33]

; #define LAS __attribute__((address_space(3)))
; __device__ __forceinline__ unsigned cvtpk(float lo, float hi) { typedef __bf16 bf16x2_t __attribute__((ext_vector_type(2))); f32x2 v = {lo, hi}; bf16x2_t b = __builtin_convertvector(v, bf16x2_t); return __builtin_bit_cast(unsigned, b); }
; template <bool BAND>
; __device__ __forceinline__ void tile_body(f32x16* o, float& l_reg, const bf16x8* qr, const LAS unsigned char* kbs, const LAS float* wb, int vb, float ci, int hi, int keybase, int qabs) {
;     f32x16 p0, p1;
; #pragma unroll
;     for (int g4 = 0; g4 < 4; ++g4) {
;         const f32x4 ba = *(const LAS f32x4*)(wb + 8 * g4 + 4 * hi) + ci, bb = *(const LAS f32x4*)(wb + 32 + 8 * g4 + 4 * hi) + ci;
; #pragma unroll
;         for (int e = 0; e < 4; ++e) { p0[4 * g4 + e] = ba[e]; p1[4 * g4 + e] = bb[e]; }
;     }
; #pragma unroll
;     for (int d0 = 0; d0 < 4; ++d0) {
;         const bf16x8 b0 = *(const LAS bf16x8*)(kbs + d0 * 2048), b1 = *(const LAS bf16x8*)(kbs + d0 * 2048 + 512);
;         p0 = __builtin_amdgcn_mfma_f32_32x32x16_bf16(b0, qr[d0], p0, 0, 0, 0); p1 = __builtin_amdgcn_mfma_f32_32x32x16_bf16(b1, qr[d0], p1, 0, 0, 0); }
;     if (BAND) {
; #pragma unroll
;         for (int r = 0; r < 16; ++r) { const int key = keybase + 8 * (r >> 2) + (r & 3); if (key > qabs) p0[r] = -INFINITY; if (key + 32 > qabs) p1[r] = -INFINITY; }
;     }
;     f32x2 s2 = {0.f, 0.f};
; #pragma unroll
;     for (int r = 0; r < 16; r += 2) {
;         p0[r] = __builtin_amdgcn_exp2f(p0[r]); p0[r + 1] = __builtin_amdgcn_exp2f(p0[r + 1]); p1[r] = __builtin_amdgcn_exp2f(p1[r]); p1[r + 1] = __builtin_amdgcn_exp2f(p1[r + 1]);
;         s2 += (f32x2){p0[r], p0[r + 1]}; s2 += (f32x2){p1[r], p1[r + 1]}; }
;     l_reg += s2.x + s2.y;
;     u32x4 pw0, pw1, pw2, pw3;
;     pw0 = (u32x4){cvtpk(p0[0], p0[1]), cvtpk(p0[2], p0[3]), cvtpk(p0[4], p0[5]), cvtpk(p0[6], p0[7])};
;     pw1 = (u32x4){cvtpk(p0[8], p0[9]), cvtpk(p0[10], p0[11]), cvtpk(p0[12], p0[13]), cvtpk(p0[14], p0[15])};
;     pw2 = (u32x4){cvtpk(p1[0], p1[1]), cvtpk(p1[2], p1[3]), cvtpk(p1[4], p1[5]), cvtpk(p1[6], p1[7])};
;     pw3 = (u32x4){cvtpk(p1[8], p1[9]), cvtpk(p1[10], p1[11]), cvtpk(p1[12], p1[13]), cvtpk(p1[14], p1[15])};
;     pv(o, vb, __builtin_bit_cast(bf16x8, pw0), __builtin_bit_cast(bf16x8, pw1), __builtin_bit_cast(bf16x8, pw2), __builtin_bit_cast(bf16x8, pw3));
.LBB0_792:
	s_cmp_lg_u32 s48, 0
	v_fma_f32 v151, v150, s50, -v146
	s_cselect_b64 s[64:65], -1, 0
	v_cmp_nlt_f32_e64 s[66:67], v151, -v131
	v_fma_f32 v196, v150, s50, -v197
	v_cmp_lt_f32_e64 s[100:101], v196, -v131
	s_nop 3
	s_or_b64 s[98:99], s[98:99], s[100:101]
	s_and_b64 s[68:69], s[64:65], s[66:67]
	s_mov_b64 s[66:67], -1
	s_and_saveexec_b64 s[64:65], s[68:69]
	s_cbranch_execz .LBB0_776
	s_waitcnt lgkmcnt(0)
	s_barrier
	s_waitcnt vmcnt(8)
	s_nop 1
	v_add_f32_dpp v151, v141, v141 row_shl:1 row_mask:0xf bank_mask:0xf bound_ctrl:1
	s_nop 1
	v_add_f32_dpp v151, v151, v151 row_shl:2 row_mask:0xf bank_mask:0xf bound_ctrl:1
	s_nop 1
	v_add_f32_dpp v151, v151, v151 row_shl:4 row_mask:0xf bank_mask:0xf bound_ctrl:1
	s_nop 1
	v_add_f32_dpp v152, v151, v151 row_shl:8 row_mask:0xf bank_mask:0xf bound_ctrl:1
	s_nop 0
	v_readlane_b32 s28, v152, 16
	v_readlane_b32 s79, v152, 32
	v_readlane_b32 s77, v152, 48
	s_nop 0
	v_mul_f32_e32 v153, s79, v192
	v_fmac_f32_e32 v153, s28, v191
	v_fmac_f32_e32 v153, s77, v193
	v_add_f32_e32 v151, s76, v150
	v_add_f32_e32 v150, v152, v153
	v_add_f32_e32 v152, v151, v150
	s_lshl_b32 s28, s70, 8
	v_sub_f32_e32 v141, v152, v141
	s_add_i32 s76, s53, s28
	v_mul_f32_e32 v141, 0x3fb8aa3b, v141
	v_lshl_add_u32 v152, v137, 2, s76
	s_lshl_b32 s77, s70, 14
	ds_write_b32 v152, v141 offset:32768
	v_add_u32_e32 v141, s77, v143
	s_max_i32 s28, s48, 5
	s_waitcnt vmcnt(4)
	ds_write_b128 v141, v[70:73]
	ds_write_b128 v141, v[82:85] offset:8192
	s_add_i32 s28, s28, -5
	s_waitcnt lgkmcnt(0)
	s_lshl_b64 s[66:67], s[28:29], 11
	v_lshl_add_u64 v[70:71], v[110:111], 0, s[66:67]
	global_load_dword v141, v[70:71], off
	s_lshl_b64 s[66:67], s[28:29], 16
	v_lshl_add_u64 v[82:83], v[106:107], 0, s[66:67]
	global_load_dwordx4 v[70:73], v[82:83], off
	v_lshl_add_u64 v[152:153], v[108:109], 0, s[66:67]
	global_load_dwordx4 v[82:85], v[152:153], off
	v_readfirstlane_b32 s79, v150
	s_and_b64 vcc, exec, s[12:13]
	s_cbranch_vccnz .LBB0_808
	s_and_b64 vcc, exec, s[98:99]
	s_cbranch_vccnz .LBB0_808
	s_add_i32 s28, s75, 0xffffff80
	s_cmp_gt_i32 s28, s73
	s_cbranch_scc1 .LBB0_808
	s_cmp_le_i32 s48, s72
	v_add_u32_e32 v150, s78, v144
	s_mov_b64 s[66:67], -1
	v_add_u32_e32 v152, s78, v145
	v_lshl_add_u32 v153, v142, 2, s71
	s_cbranch_scc0 .LBB0_805
	ds_read_b128 v[34:37], v153 offset:32768
	ds_read_b128 v[38:41], v153 offset:32800
	ds_read_b128 v[42:45], v153 offset:32832
	ds_read_b128 v[46:49], v153 offset:32864
	ds_read_b128 v[50:53], v153 offset:32896
	ds_read_b128 v[54:57], v153 offset:32928
	ds_read_b128 v[58:61], v153 offset:32960
	ds_read_b128 v[62:65], v153 offset:32992
	ds_read_b128 v[154:157], v152
	ds_read_b128 v[158:161], v152 offset:512
	s_waitcnt lgkmcnt(6)
	ds_read_b128 v[210:213], v152 offset:2048
	ds_read_b128 v[214:217], v152 offset:2560
	ds_read_b128 v[218:221], v152 offset:4096
	ds_read_b128 v[222:225], v152 offset:4608
	ds_read_b128 v[226:229], v152 offset:6144
	ds_read_b128 v[230:233], v152 offset:6656
	v_pk_add_f32 v[48:49], v[126:127], v[48:49]
	v_pk_add_f32 v[44:45], v[122:123], v[44:45]
	v_pk_add_f32 v[40:41], v[118:119], v[40:41]
	v_pk_add_f32 v[36:37], v[114:115], v[36:37]
	v_pk_add_f32 v[46:47], v[124:125], v[46:47]
	v_pk_add_f32 v[42:43], v[120:121], v[42:43]
	v_pk_add_f32 v[38:39], v[116:117], v[38:39]
	v_pk_add_f32 v[34:35], v[112:113], v[34:35]
	s_waitcnt lgkmcnt(8)
	v_pk_add_f32 v[64:65], v[126:127], v[64:65]
	v_pk_add_f32 v[60:61], v[122:123], v[60:61]
	s_waitcnt lgkmcnt(7)
	v_mfma_f32_32x32x16_bf16 v[34:49], v[154:157], v[94:97], v[34:49]
	v_add_f32_e64 v56, v118, v56
	v_add_f32_e64 v57, v119, v57
	v_add_f32_e64 v52, v114, v52
	v_add_f32_e64 v53, v115, v53
	v_add_f32_e64 v62, v124, v62
	v_add_f32_e64 v63, v125, v63
	v_pk_add_f32 v[58:59], v[120:121], v[58:59]
	v_pk_add_f32 v[54:55], v[116:117], v[54:55]
	v_pk_add_f32 v[50:51], v[112:113], v[50:51]
	s_waitcnt lgkmcnt(6)
	s_nop 0
	v_mfma_f32_32x32x16_bf16 v[50:65], v[158:161], v[94:97], v[50:65]
	s_waitcnt lgkmcnt(5)
	v_mfma_f32_32x32x16_bf16 v[34:49], v[210:213], v[98:101], v[34:49]
	s_waitcnt lgkmcnt(4)
	v_mfma_f32_32x32x16_bf16 v[50:65], v[214:217], v[98:101], v[50:65]
	s_waitcnt lgkmcnt(3)
	v_mfma_f32_32x32x16_bf16 v[34:49], v[218:221], v[102:105], v[34:49]
	s_waitcnt lgkmcnt(2)
	v_mfma_f32_32x32x16_bf16 v[50:65], v[222:225], v[102:105], v[50:65]
	s_waitcnt lgkmcnt(1)
	v_mfma_f32_32x32x16_bf16 v[34:49], v[226:229], v[90:93], v[34:49]
	s_waitcnt lgkmcnt(0)
	v_mfma_f32_32x32x16_bf16 v[50:65], v[230:233], v[90:93], v[50:65]
	s_nop 9
	v_exp_f32_e32 v34, v34
	v_exp_f32_e32 v35, v35
	v_exp_f32_e32 v36, v36
	v_exp_f32_e32 v37, v37
	v_exp_f32_e32 v38, v38
	v_pk_add_f32 v[154:155], v[34:35], 0 op_sel_hi:[1,0]
	v_exp_f32_e32 v39, v39
	v_exp_f32_e32 v50, v50
	v_exp_f32_e32 v51, v51
	v_exp_f32_e32 v52, v52
	v_exp_f32_e32 v53, v53
	v_exp_f32_e32 v54, v54
	v_pk_add_f32 v[154:155], v[50:51], v[154:155]
	v_exp_f32_e32 v55, v55
	v_pk_add_f32 v[154:155], v[36:37], v[154:155]
	v_exp_f32_e32 v40, v40
	v_exp_f32_e32 v41, v41
	v_pk_add_f32 v[154:155], v[52:53], v[154:155]
	v_exp_f32_e32 v56, v56
	v_exp_f32_e32 v57, v57
	v_pk_add_f32 v[154:155], v[38:39], v[154:155]
	v_exp_f32_e32 v42, v42
	v_exp_f32_e32 v43, v43
	v_pk_add_f32 v[154:155], v[54:55], v[154:155]
	v_exp_f32_e32 v58, v58
	v_exp_f32_e32 v59, v59
	v_pk_add_f32 v[154:155], v[40:41], v[154:155]
	v_exp_f32_e32 v44, v44
	v_exp_f32_e32 v45, v45
	v_pk_add_f32 v[154:155], v[56:57], v[154:155]
	v_exp_f32_e32 v60, v60
	v_exp_f32_e32 v61, v61
	v_pk_add_f32 v[154:155], v[42:43], v[154:155]
	v_exp_f32_e32 v46, v46
	v_exp_f32_e32 v47, v47
	v_cvt_pk_bf16_f32 v164, v50, v51
	ds_read_b64_tr_b16 v[50:51],v150 offset:0
	v_pk_add_f32 v[154:155], v[58:59], v[154:155]
	v_exp_f32_e32 v62, v62
	v_exp_f32_e32 v63, v63
	v_cvt_pk_bf16_f32 v165, v52, v53
	ds_read_b64_tr_b16 v[52:53],v150 offset:512
	v_pk_add_f32 v[154:155], v[44:45], v[154:155]
	v_exp_f32_e32 v48, v48
	v_exp_f32_e32 v49, v49
	v_cvt_pk_bf16_f32 v166, v54, v55
	ds_read_b64_tr_b16 v[54:55],v150 offset:1024
	v_pk_add_f32 v[154:155], v[60:61], v[154:155]
	v_exp_f32_e32 v64, v64
	v_exp_f32_e32 v65, v65
	v_cvt_pk_bf16_f32 v167, v56, v57
	ds_read_b64_tr_b16 v[56:57],v150 offset:1536
	v_pk_add_f32 v[154:155], v[46:47], v[154:155]
	v_cvt_pk_bf16_f32 v168, v58, v59
	ds_read_b64_tr_b16 v[58:59],v150 offset:2048
	v_pk_add_f32 v[154:155], v[62:63], v[154:155]
	v_cvt_pk_bf16_f32 v169, v60, v61
	ds_read_b64_tr_b16 v[60:61],v150 offset:2560
	v_pk_add_f32 v[154:155], v[48:49], v[154:155]
	v_cvt_pk_bf16_f32 v170, v62, v63
	ds_read_b64_tr_b16 v[62:63],v150 offset:3072
	v_pk_add_f32 v[154:155], v[64:65], v[154:155]
	v_cvt_pk_bf16_f32 v171, v64, v65
	ds_read_b64_tr_b16 v[64:65],v150 offset:3584
	s_waitcnt lgkmcnt(0)
; #define LAS __attribute__((address_space(3)))
; __device__ __forceinline__ void pv(f32x16* o, int vb, bf16x8 pa0, bf16x8 pa1, bf16x8 pa2, bf16x8 pa3) {
; #pragma unroll
;     for (int d0 = 0; d0 < 2; ++d0) { s16x4 lo[4], hi[4];
; #pragma unroll
;         for (int ks = 0; ks < 4; ++ks) {
;             asm volatile("ds_read_b64_tr_b16 %0,%1 offset:%c2" : "=&v"(lo[ks]) : "v"(vb), "i"(d0 * 4096 + ks * 1024) : "memory");
;             asm volatile("ds_read_b64_tr_b16 %0,%1 offset:%c2" : "=&v"(hi[ks]) : "v"(vb), "i"(d0 * 4096 + ks * 1024 + 512) : "memory"); }
;         asm volatile("s_waitcnt lgkmcnt(0)" ::: "memory"); __builtin_amdgcn_sched_barrier(0);
;     ...
;         o[d0] = __builtin_amdgcn_mfma_f32_32x32x16_bf16(pa0, PK(0), o[d0], 0, 0, 0);
;         o[d0] = __builtin_amdgcn_mfma_f32_32x32x16_bf16(pa1, PK(1), o[d0], 0, 0, 0);
;         o[d0] = __builtin_amdgcn_mfma_f32_32x32x16_bf16(pa2, PK(2), o[d0], 0, 0, 0);
;         o[d0] = __builtin_amdgcn_mfma_f32_32x32x16_bf16(pa3, PK(3), o[d0], 0, 0, 0);
;     ...
;     }
; template <bool BAND>
; __device__ __forceinline__ void tile_body(f32x16* o, float& l_reg, const bf16x8* qr, const LAS unsigned char* kbs, const LAS float* wb, int vb, float ci, int hi, int keybase, int qabs) {
;     f32x16 p0, p1;
; #pragma unroll
;     for (int g4 = 0; g4 < 4; ++g4) {
;         const f32x4 ba = *(const LAS f32x4*)(wb + 8 * g4 + 4 * hi) + ci, bb = *(const LAS f32x4*)(wb + 32 + 8 * g4 + 4 * hi) + ci;
; #pragma unroll
;         for (int e = 0; e < 4; ++e) { p0[4 * g4 + e] = ba[e]; p1[4 * g4 + e] = bb[e]; }
;     }
; #pragma unroll
;     for (int d0 = 0; d0 < 4; ++d0) {
;         const bf16x8 b0 = *(const LAS bf16x8*)(kbs + d0 * 2048), b1 = *(const LAS bf16x8*)(kbs + d0 * 2048 + 512);
;         p0 = __builtin_amdgcn_mfma_f32_32x32x16_bf16(b0, qr[d0], p0, 0, 0, 0); p1 = __builtin_amdgcn_mfma_f32_32x32x16_bf16(b1, qr[d0], p1, 0, 0, 0); }
;     if (BAND) {
; #pragma unroll
;         for (int r = 0; r < 16; ++r) { const int key = keybase + 8 * (r >> 2) + (r & 3); if (key > qabs) p0[r] = -INFINITY; if (key + 32 > qabs) p1[r] = -INFINITY; }
	v_add_f32_e32 v154, v154, v155
	v_add_f32_e32 v154, v148, v154
	v_cvt_pk_bf16_f32 v156, v34, v35
	v_cvt_pk_bf16_f32 v157, v36, v37
	v_cvt_pk_bf16_f32 v158, v38, v39
	v_cvt_pk_bf16_f32 v159, v40, v41
	v_cvt_pk_bf16_f32 v160, v42, v43
	v_cvt_pk_bf16_f32 v161, v44, v45
	v_cvt_pk_bf16_f32 v162, v46, v47
	v_cvt_pk_bf16_f32 v163, v48, v49
	v_mfma_f32_32x32x16_bf16 v[2:17], v[156:159], v[50:53], v[2:17]
	ds_read_b64_tr_b16 v[172:173],v150 offset:4096
	ds_read_b64_tr_b16 v[174:175],v150 offset:4608
	ds_read_b64_tr_b16 v[176:177],v150 offset:5120
	ds_read_b64_tr_b16 v[178:179],v150 offset:5632
	ds_read_b64_tr_b16 v[180:181],v150 offset:6144
	ds_read_b64_tr_b16 v[182:183],v150 offset:6656
	ds_read_b64_tr_b16 v[184:185],v150 offset:7168
	s_nop 0
	v_mfma_f32_32x32x16_bf16 v[2:17], v[160:163], v[54:57], v[2:17]
	ds_read_b64_tr_b16 v[186:187],v150 offset:7680
	s_nop 0
	v_mfma_f32_32x32x16_bf16 v[2:17], v[164:167], v[58:61], v[2:17]
	v_mfma_f32_32x32x16_bf16 v[2:17], v[168:171], v[62:65], v[2:17]
	s_waitcnt lgkmcnt(6)
	v_mfma_f32_32x32x16_bf16 v[18:33], v[156:159], v[172:175], v[18:33]
	s_mov_b64 s[66:67], 0
	s_waitcnt lgkmcnt(4)
	v_mfma_f32_32x32x16_bf16 v[18:33], v[160:163], v[176:179], v[18:33]
	s_waitcnt lgkmcnt(2)
	v_mfma_f32_32x32x16_bf16 v[18:33], v[164:167], v[180:183], v[18:33]
	s_waitcnt lgkmcnt(0)
	v_mfma_f32_32x32x16_bf16 v[18:33], v[168:171], v[184:187], v[18:33]
.LBB0_805:
	s_andn2_b64 vcc, exec, s[66:67]
	s_cbranch_vccnz .Lmy_attjoin_B
	s_nop 4
	ds_read_b128 v[34:37], v153 offset:32768
	ds_read_b128 v[38:41], v153 offset:32800
	ds_read_b128 v[42:45], v153 offset:32832
	ds_read_b128 v[46:49], v153 offset:32864
	s_nop 0
	ds_read_b128 v[50:53], v153 offset:32896
	ds_read_b128 v[54:57], v153 offset:32928
	ds_read_b128 v[58:61], v153 offset:32960
	ds_read_b128 v[62:65], v153 offset:32992
	ds_read_b128 v[154:157], v152
	ds_read_b128 v[158:161], v152 offset:512
	s_waitcnt lgkmcnt(4)
	ds_read_b128 v[210:213], v152 offset:2048
	ds_read_b128 v[214:217], v152 offset:2560
	ds_read_b128 v[218:221], v152 offset:4096
	ds_read_b128 v[222:225], v152 offset:4608
	ds_read_b128 v[226:229], v152 offset:6656
	ds_read_b128 v[230:233], v152 offset:6144
	v_pk_add_f32 v[56:57], v[118:119], v[56:57]
	s_waitcnt lgkmcnt(9)
	v_pk_add_f32 v[60:61], v[122:123], v[60:61]
	s_waitcnt lgkmcnt(8)
	v_pk_add_f32 v[64:65], v[126:127], v[64:65]
	v_pk_add_f32 v[52:53], v[114:115], v[52:53]
	v_pk_add_f32 v[62:63], v[124:125], v[62:63]
	v_pk_add_f32 v[58:59], v[120:121], v[58:59]
	v_pk_add_f32 v[54:55], v[116:117], v[54:55]
	v_pk_add_f32 v[50:51], v[112:113], v[50:51]
	v_pk_add_f32 v[48:49], v[126:127], v[48:49]
	v_pk_add_f32 v[44:45], v[122:123], v[44:45]
	v_pk_add_f32 v[40:41], v[118:119], v[40:41]
	v_pk_add_f32 v[36:37], v[114:115], v[36:37]
	v_pk_add_f32 v[46:47], v[124:125], v[46:47]
	v_pk_add_f32 v[42:43], v[120:121], v[42:43]
	v_pk_add_f32 v[38:39], v[116:117], v[38:39]
	v_pk_add_f32 v[34:35], v[112:113], v[34:35]
	s_waitcnt lgkmcnt(6)
	v_mfma_f32_32x32x16_bf16 v[50:65], v[158:161], v[94:97], v[50:65]
	v_mfma_f32_32x32x16_bf16 v[34:49], v[154:157], v[94:97], v[34:49]
	s_waitcnt lgkmcnt(4)
	v_mfma_f32_32x32x16_bf16 v[50:65], v[214:217], v[98:101], v[50:65]
	v_mfma_f32_32x32x16_bf16 v[34:49], v[210:213], v[98:101], v[34:49]
	s_waitcnt lgkmcnt(2)
	v_mfma_f32_32x32x16_bf16 v[50:65], v[222:225], v[102:105], v[50:65]
	v_mfma_f32_32x32x16_bf16 v[34:49], v[218:221], v[102:105], v[34:49]
	v_add_u32_e32 v152, s75, v142
	v_add_u32_e32 v153, 0xffffff80, v152
	s_waitcnt lgkmcnt(1)
	v_mfma_f32_32x32x16_bf16 v[50:65], v[226:229], v[90:93], v[50:65]
	v_add_u32_e32 v154, 0xffffffa0, v152
	v_cmp_le_i32_e32 vcc, v154, v147
	s_waitcnt lgkmcnt(0)
; __device__ __forceinline__ void pv(f32x16* o, int vb, bf16x8 pa0, bf16x8 pa1, bf16x8 pa2, bf16x8 pa3) {
; #pragma unroll
;     for (int d0 = 0; d0 < 2; ++d0) { s16x4 lo[4], hi[4];
; #pragma unroll
;         for (int ks = 0; ks < 4; ++ks) {
;             asm volatile("ds_read_b64_tr_b16 %0,%1 offset:%c2" : "=&v"(lo[ks]) : "v"(vb), "i"(d0 * 4096 + ks * 1024) : "memory");
;             asm volatile("ds_read_b64_tr_b16 %0,%1 offset:%c2" : "=&v"(hi[ks]) : "v"(vb), "i"(d0 * 4096 + ks * 1024 + 512) : "memory"); }
;         asm volatile("s_waitcnt lgkmcnt(0)" ::: "memory"); __builtin_amdgcn_sched_barrier(0);
;     ...
;         o[d0] = __builtin_amdgcn_mfma_f32_32x32x16_bf16(pa0, PK(0), o[d0], 0, 0, 0);
;         o[d0] = __builtin_amdgcn_mfma_f32_32x32x16_bf16(pa1, PK(1), o[d0], 0, 0, 0);
;         o[d0] = __builtin_amdgcn_mfma_f32_32x32x16_bf16(pa2, PK(2), o[d0], 0, 0, 0);
;         o[d0] = __builtin_amdgcn_mfma_f32_32x32x16_bf16(pa3, PK(3), o[d0], 0, 0, 0);
;     ...
;     }
; template <bool BAND>
; __device__ __forceinline__ void tile_body(f32x16* o, float& l_reg, const bf16x8* qr, const LAS unsigned char* kbs, const LAS float* wb, int vb, float ci, int hi, int keybase, int qabs) {
;     ...
;     if (BAND) {
; #pragma unroll
;         for (int r = 0; r < 16; ++r) { const int key = keybase + 8 * (r >> 2) + (r & 3); if (key > qabs) p0[r] = -INFINITY; if (key + 32 > qabs) p1[r] = -INFINITY; }
;     }
;     f32x2 s2 = {0.f, 0.f};
; #pragma unroll
;     for (int r = 0; r < 16; r += 2) {
;         p0[r] = __builtin_amdgcn_exp2f(p0[r]); p0[r + 1] = __builtin_amdgcn_exp2f(p0[r + 1]); p1[r] = __builtin_amdgcn_exp2f(p1[r]); p1[r + 1] = __builtin_amdgcn_exp2f(p1[r + 1]);
;         s2 += (f32x2){p0[r], p0[r + 1]}; s2 += (f32x2){p1[r], p1[r + 1]}; }
;     l_reg += s2.x + s2.y;
;     u32x4 pw0, pw1, pw2, pw3;
;     pw0 = (u32x4){cvtpk(p0[0], p0[1]), cvtpk(p0[2], p0[3]), cvtpk(p0[4], p0[5]), cvtpk(p0[6], p0[7])};
;     pw1 = (u32x4){cvtpk(p0[8], p0[9]), cvtpk(p0[10], p0[11]), cvtpk(p0[12], p0[13]), cvtpk(p0[14], p0[15])};
;     pw2 = (u32x4){cvtpk(p1[0], p1[1]), cvtpk(p1[2], p1[3]), cvtpk(p1[4], p1[5]), cvtpk(p1[6], p1[7])};
;     pw3 = (u32x4){cvtpk(p1[8], p1[9]), cvtpk(p1[10], p1[11]), cvtpk(p1[12], p1[13]), cvtpk(p1[14], p1[15])};
;     pv(o, vb, __builtin_bit_cast(bf16x8, pw0), __builtin_bit_cast(bf16x8, pw1), __builtin_bit_cast(bf16x8, pw2), __builtin_bit_cast(bf16x8, pw3));
	v_mfma_f32_32x32x16_bf16 v[34:49], v[230:233], v[90:93], v[34:49]
	s_nop 7
	v_cndmask_b32_e32 v50, v134, v50, vcc
	v_cmp_lt_i32_e32 vcc, v153, v147
	s_nop 1
	v_cndmask_b32_e32 v35, v134, v35, vcc
	v_cmp_le_i32_e32 vcc, v153, v147
	v_add_u32_e32 v153, 0xffffffa1, v152
	v_exp_f32_e32 v35, v35
	v_cndmask_b32_e32 v34, v134, v34, vcc
	v_cmp_le_i32_e32 vcc, v153, v147
	v_add_u32_e32 v153, 0xffffff82, v152
	v_exp_f32_e32 v34, v34
	v_cndmask_b32_e32 v51, v134, v51, vcc
	v_cmp_le_i32_e32 vcc, v153, v147
	v_add_u32_e32 v153, 0xffffffa2, v152
	s_nop 0
	v_cndmask_b32_e32 v36, v134, v36, vcc
	v_cmp_le_i32_e32 vcc, v153, v147
	v_add_u32_e32 v153, 0xffffff83, v152
	v_exp_f32_e32 v36, v36
	v_cndmask_b32_e32 v52, v134, v52, vcc
	v_cmp_le_i32_e32 vcc, v153, v147
	v_add_u32_e32 v153, 0xffffffa3, v152
	s_nop 0
	v_cndmask_b32_e32 v37, v134, v37, vcc
	v_cmp_le_i32_e32 vcc, v153, v147
	v_add_u32_e32 v153, 0xffffff88, v152
	v_exp_f32_e32 v37, v37
	v_cndmask_b32_e32 v53, v134, v53, vcc
	v_cmp_le_i32_e32 vcc, v153, v147
	s_nop 1
	v_cndmask_b32_e32 v153, v134, v38, vcc
	v_add_u32_e32 v38, 0xffffffa8, v152
	v_cmp_le_i32_e32 vcc, v38, v147
	v_add_u32_e32 v38, 0xffffff89, v152
	s_nop 0
	v_cndmask_b32_e32 v54, v134, v54, vcc
	v_cmp_le_i32_e32 vcc, v38, v147
	v_add_u32_e32 v38, 0xffffffa9, v152
	s_nop 0
	v_cndmask_b32_e32 v154, v134, v39, vcc
	v_cmp_le_i32_e32 vcc, v38, v147
	v_add_u32_e32 v38, 0xffffff8a, v152
	s_nop 0
	v_cndmask_b32_e32 v55, v134, v55, vcc
	v_cmp_le_i32_e32 vcc, v38, v147
	v_add_u32_e32 v38, 0xffffffaa, v152
	s_nop 0
	v_cndmask_b32_e32 v155, v134, v40, vcc
	v_cmp_le_i32_e32 vcc, v38, v147
	v_add_u32_e32 v38, 0xffffff8b, v152
	v_exp_f32_e32 v40, v153
	v_cndmask_b32_e32 v56, v134, v56, vcc
	v_cmp_le_i32_e32 vcc, v38, v147
	v_add_u32_e32 v38, 0xffffffab, v152
	s_nop 0
	v_cndmask_b32_e32 v156, v134, v41, vcc
	v_cmp_le_i32_e32 vcc, v38, v147
	v_add_u32_e32 v38, 0xffffff90, v152
	v_exp_f32_e32 v41, v154
	v_cndmask_b32_e32 v57, v134, v57, vcc
	v_cmp_le_i32_e32 vcc, v38, v147
	v_add_u32_e32 v38, 0xffffffb0, v152
	s_nop 0
	v_cndmask_b32_e32 v157, v134, v42, vcc
	v_cmp_le_i32_e32 vcc, v38, v147
	v_add_u32_e32 v38, 0xffffff91, v152
	v_exp_f32_e32 v42, v50
	v_cndmask_b32_e32 v58, v134, v58, vcc
	v_cmp_le_i32_e32 vcc, v38, v147
	v_add_u32_e32 v38, 0xffffffb1, v152
	v_exp_f32_e32 v50, v56
	v_cndmask_b32_e32 v158, v134, v43, vcc
	v_cmp_le_i32_e32 vcc, v38, v147
	v_add_u32_e32 v38, 0xffffff92, v152
	v_exp_f32_e32 v43, v51
	v_cndmask_b32_e32 v59, v134, v59, vcc
	v_cmp_le_i32_e32 vcc, v38, v147
	v_add_u32_e32 v38, 0xffffffb2, v152
	v_exp_f32_e32 v51, v57
	v_cndmask_b32_e32 v159, v134, v44, vcc
	v_cmp_le_i32_e32 vcc, v38, v147
	v_add_u32_e32 v38, 0xffffff93, v152
	v_exp_f32_e32 v44, v52
	v_cndmask_b32_e32 v60, v134, v60, vcc
	v_cmp_le_i32_e32 vcc, v38, v147
	v_add_u32_e32 v38, 0xffffffb3, v152
	v_exp_f32_e32 v52, v157
	v_cndmask_b32_e32 v160, v134, v45, vcc
	v_cmp_le_i32_e32 vcc, v38, v147
	v_add_u32_e32 v38, 0xffffff98, v152
	v_exp_f32_e32 v45, v53
	v_cndmask_b32_e32 v61, v134, v61, vcc
	v_cmp_le_i32_e32 vcc, v38, v147
	v_add_u32_e32 v38, 0xffffffb8, v152
	v_exp_f32_e32 v53, v158
	v_cndmask_b32_e32 v161, v134, v46, vcc
	v_cmp_le_i32_e32 vcc, v38, v147
	v_add_u32_e32 v38, 0xffffff99, v152
	v_exp_f32_e32 v46, v54
	v_cndmask_b32_e32 v62, v134, v62, vcc
	v_cmp_le_i32_e32 vcc, v38, v147
	v_add_u32_e32 v38, 0xffffffb9, v152
	v_exp_f32_e32 v54, v58
	v_cndmask_b32_e32 v162, v134, v47, vcc
	v_cmp_le_i32_e32 vcc, v38, v147
	v_add_u32_e32 v38, 0xffffff9a, v152
	v_exp_f32_e32 v47, v55
	v_cndmask_b32_e32 v63, v134, v63, vcc
	v_cmp_le_i32_e32 vcc, v38, v147
	v_add_u32_e32 v38, 0xffffffba, v152
	v_exp_f32_e32 v55, v59
	v_cndmask_b32_e32 v163, v134, v48, vcc
	v_cmp_le_i32_e32 vcc, v38, v147
	v_add_u32_e32 v38, 0xffffff9b, v152
	v_exp_f32_e32 v48, v155
	v_cndmask_b32_e32 v164, v134, v64, vcc
	v_cmp_le_i32_e32 vcc, v38, v147
	v_add_u32_e32 v38, 0xffffffbb, v152
	v_exp_f32_e32 v56, v159
	v_cndmask_b32_e32 v165, v134, v49, vcc
	v_cmp_le_i32_e32 vcc, v38, v147
	v_pk_add_f32 v[38:39], v[34:35], 0 op_sel_hi:[1,0]
	v_exp_f32_e32 v49, v156
	v_pk_add_f32 v[38:39], v[42:43], v[38:39]
	v_exp_f32_e32 v57, v160
	v_pk_add_f32 v[38:39], v[36:37], v[38:39]
	v_exp_f32_e32 v58, v60
	v_pk_add_f32 v[38:39], v[44:45], v[38:39]
	v_exp_f32_e32 v59, v61
	v_pk_add_f32 v[38:39], v[40:41], v[38:39]
	v_exp_f32_e32 v60, v161
	v_pk_add_f32 v[38:39], v[46:47], v[38:39]
	v_exp_f32_e32 v61, v162
	v_pk_add_f32 v[38:39], v[48:49], v[38:39]
	v_exp_f32_e32 v62, v62
	v_pk_add_f32 v[38:39], v[50:51], v[38:39]
	v_exp_f32_e32 v63, v63
	v_pk_add_f32 v[38:39], v[52:53], v[38:39]
	v_cndmask_b32_e32 v166, v134, v65, vcc
	v_pk_add_f32 v[38:39], v[54:55], v[38:39]
	v_exp_f32_e32 v64, v163
	v_pk_add_f32 v[38:39], v[56:57], v[38:39]
	v_exp_f32_e32 v65, v165
	v_pk_add_f32 v[38:39], v[58:59], v[38:39]
	v_exp_f32_e32 v152, v164
	v_exp_f32_e32 v153, v166
	v_pk_add_f32 v[38:39], v[60:61], v[38:39]
	v_cvt_pk_bf16_f32 v42, v42, v43
	v_pk_add_f32 v[38:39], v[62:63], v[38:39]
	v_cvt_pk_bf16_f32 v43, v44, v45
	v_pk_add_f32 v[38:39], v[64:65], v[38:39]
	v_cvt_pk_bf16_f32 v45, v50, v51
	v_pk_add_f32 v[38:39], v[152:153], v[38:39]
	ds_read_b64_tr_b16 v[50:51],v150 offset:0
	v_cvt_pk_bf16_f32 v44, v46, v47
	v_add_f32_e32 v38, v38, v39
	v_add_f32_e32 v154, v148, v38
	v_cvt_pk_bf16_f32 v38, v52, v53
	ds_read_b64_tr_b16 v[52:53],v150 offset:512
	v_cvt_pk_bf16_f32 v46, v54, v55
	ds_read_b64_tr_b16 v[54:55],v150 offset:1024
	v_cvt_pk_bf16_f32 v39, v56, v57
	ds_read_b64_tr_b16 v[56:57],v150 offset:1536
	v_cvt_pk_bf16_f32 v47, v58, v59
	ds_read_b64_tr_b16 v[58:59],v150 offset:2048
	v_cvt_pk_bf16_f32 v34, v34, v35
	v_cvt_pk_bf16_f32 v35, v36, v37
	v_cvt_pk_bf16_f32 v36, v40, v41
	v_cvt_pk_bf16_f32 v40, v60, v61
	ds_read_b64_tr_b16 v[60:61],v150 offset:2560
	v_cvt_pk_bf16_f32 v37, v48, v49
	v_cvt_pk_bf16_f32 v48, v62, v63
	ds_read_b64_tr_b16 v[62:63],v150 offset:3072
	v_cvt_pk_bf16_f32 v41, v64, v65
	ds_read_b64_tr_b16 v[64:65],v150 offset:3584
	s_waitcnt lgkmcnt(0)
	v_cvt_pk_bf16_f32 v49, v152, v153
	v_mfma_f32_32x32x16_bf16 v[2:17], v[34:37], v[50:53], v[2:17]
	ds_read_b64_tr_b16 v[50:51],v150 offset:4096
	ds_read_b64_tr_b16 v[52:53],v150 offset:4608
	v_mfma_f32_32x32x16_bf16 v[2:17], v[38:41], v[54:57], v[2:17]
	ds_read_b64_tr_b16 v[54:55],v150 offset:5120
	ds_read_b64_tr_b16 v[56:57],v150 offset:5632
	v_mfma_f32_32x32x16_bf16 v[2:17], v[42:45], v[58:61], v[2:17]
	ds_read_b64_tr_b16 v[58:59],v150 offset:6144
	ds_read_b64_tr_b16 v[60:61],v150 offset:6656
	ds_read_b64_tr_b16 v[156:157],v150 offset:7168
	ds_read_b64_tr_b16 v[158:159],v150 offset:7680
	s_nop 0
	v_mfma_f32_32x32x16_bf16 v[2:17], v[46:49], v[62:65], v[2:17]
	s_waitcnt lgkmcnt(6)
	v_mfma_f32_32x32x16_bf16 v[18:33], v[34:37], v[50:53], v[18:33]
	s_waitcnt lgkmcnt(4)
	v_mfma_f32_32x32x16_bf16 v[18:33], v[38:41], v[54:57], v[18:33]
	s_waitcnt lgkmcnt(2)
	v_mfma_f32_32x32x16_bf16 v[18:33], v[42:45], v[58:61], v[18:33]
	s_waitcnt lgkmcnt(0)
	v_mfma_f32_32x32x16_bf16 v[18:33], v[46:49], v[156:159], v[18:33]

; #define LAS __attribute__((address_space(3)))
; template <bool BAND>
; __device__ __forceinline__ void tile_body(f32x16* o, float& l_reg, const bf16x8* qr, const LAS unsigned char* kbs, const LAS float* wb, int vb, float ci, int hi, int keybase, int qabs) {
;     f32x16 p0, p1;
; #pragma unroll
;     for (int g4 = 0; g4 < 4; ++g4) {
;         const f32x4 ba = *(const LAS f32x4*)(wb + 8 * g4 + 4 * hi) + ci, bb = *(const LAS f32x4*)(wb + 32 + 8 * g4 + 4 * hi) + ci;
; #pragma unroll
;         for (int e = 0; e < 4; ++e) { p0[4 * g4 + e] = ba[e]; p1[4 * g4 + e] = bb[e]; }
;     }
; #pragma unroll
;     for (int d0 = 0; d0 < 4; ++d0) {
;         const bf16x8 b0 = *(const LAS bf16x8*)(kbs + d0 * 2048), b1 = *(const LAS bf16x8*)(kbs + d0 * 2048 + 512);
;         p0 = __builtin_amdgcn_mfma_f32_32x32x16_bf16(b0, qr[d0], p0, 0, 0, 0); p1 = __builtin_amdgcn_mfma_f32_32x32x16_bf16(b1, qr[d0], p1, 0, 0, 0); }
;     if (BAND) {
; #pragma unroll
;         for (int r = 0; r < 16; ++r) { const int key = keybase + 8 * (r >> 2) + (r & 3); if (key > qabs) p0[r] = -INFINITY; if (key + 32 > qabs) p1[r] = -INFINITY; }
.LBB0_819:
	s_andn2_b64 vcc, exec, s[68:69]
	s_cbranch_vccnz .LBB0_774
	s_and_b64 vcc, exec, s[98:99]
	s_cbranch_vccnz .LBB0_774
	s_add_i32 s28, s75, 0xffffff40
	s_cmp_gt_i32 s28, s73
	s_cbranch_scc1 .LBB0_774
	s_add_i32 s68, s48, -2
	s_cmp_lt_i32 s68, s72
	v_add_u32_e32 v0, s77, v144
	s_mov_b64 s[68:69], -1
	v_add_u32_e32 v149, s77, v145
	v_lshl_add_u32 v150, v142, 2, s76
	s_cbranch_scc1 .LBB0_823
	ds_read_b128 v[34:37], v150 offset:32768
	ds_read_b128 v[38:41], v150 offset:32800
	ds_read_b128 v[42:45], v150 offset:32832
	ds_read_b128 v[46:49], v150 offset:32864
	ds_read_b128 v[50:53], v150 offset:32896
	ds_read_b128 v[54:57], v150 offset:32928
	ds_read_b128 v[58:61], v150 offset:32960
	ds_read_b128 v[62:65], v150 offset:32992
	ds_read_b128 v[152:155], v149
	ds_read_b128 v[156:159], v149 offset:512
	s_waitcnt lgkmcnt(4)
	ds_read_b128 v[210:213], v149 offset:2048
	ds_read_b128 v[214:217], v149 offset:2560
	ds_read_b128 v[218:221], v149 offset:4096
	ds_read_b128 v[222:225], v149 offset:4608
	ds_read_b128 v[226:229], v149 offset:6656
	ds_read_b128 v[230:233], v149 offset:6144
	v_pk_add_f32 v[56:57], v[118:119], v[56:57]
	s_waitcnt lgkmcnt(9)
	v_pk_add_f32 v[60:61], v[122:123], v[60:61]
	s_waitcnt lgkmcnt(8)
	v_pk_add_f32 v[64:65], v[126:127], v[64:65]
	v_pk_add_f32 v[52:53], v[114:115], v[52:53]
	v_pk_add_f32 v[62:63], v[124:125], v[62:63]
	v_pk_add_f32 v[58:59], v[120:121], v[58:59]
	v_pk_add_f32 v[54:55], v[116:117], v[54:55]
	v_pk_add_f32 v[50:51], v[112:113], v[50:51]
	v_pk_add_f32 v[48:49], v[126:127], v[48:49]
	v_pk_add_f32 v[44:45], v[122:123], v[44:45]
	v_pk_add_f32 v[40:41], v[118:119], v[40:41]
	v_pk_add_f32 v[36:37], v[114:115], v[36:37]
	v_pk_add_f32 v[46:47], v[124:125], v[46:47]
	v_pk_add_f32 v[42:43], v[120:121], v[42:43]
	v_pk_add_f32 v[38:39], v[116:117], v[38:39]
	v_pk_add_f32 v[34:35], v[112:113], v[34:35]
	s_waitcnt lgkmcnt(6)
	v_mfma_f32_32x32x16_bf16 v[50:65], v[156:159], v[94:97], v[50:65]
	v_mfma_f32_32x32x16_bf16 v[34:49], v[152:155], v[94:97], v[34:49]
	s_waitcnt lgkmcnt(4)
	v_mfma_f32_32x32x16_bf16 v[50:65], v[214:217], v[98:101], v[50:65]
	v_mfma_f32_32x32x16_bf16 v[34:49], v[210:213], v[98:101], v[34:49]
	s_waitcnt lgkmcnt(2)
	v_mfma_f32_32x32x16_bf16 v[50:65], v[222:225], v[102:105], v[50:65]
	v_mfma_f32_32x32x16_bf16 v[34:49], v[218:221], v[102:105], v[34:49]
	s_waitcnt lgkmcnt(1)
	v_mfma_f32_32x32x16_bf16 v[50:65], v[226:229], v[90:93], v[50:65]
	v_add_u32_e32 v152, s75, v142
	v_add_u32_e32 v154, 0xffffff60, v152
	v_add_u32_e32 v153, 0xffffff40, v152
	v_cmp_le_i32_e32 vcc, v154, v147
	s_waitcnt lgkmcnt(0)
	v_mfma_f32_32x32x16_bf16 v[34:49], v[230:233], v[90:93], v[34:49]
	s_nop 5
	v_cndmask_b32_e32 v50, v134, v50, vcc
	v_cmp_lt_i32_e32 vcc, v153, v147
	s_nop 3
	v_cndmask_b32_e32 v35, v134, v35, vcc
	v_cmp_le_i32_e32 vcc, v153, v147
	v_add_u32_e32 v153, 0xffffff61, v152
	v_exp_f32_e32 v35, v35
	v_cndmask_b32_e32 v34, v134, v34, vcc
	v_cmp_le_i32_e32 vcc, v153, v147
	v_add_u32_e32 v153, 0xffffff42, v152
	v_exp_f32_e32 v34, v34
	v_cndmask_b32_e32 v51, v134, v51, vcc
	v_cmp_le_i32_e32 vcc, v153, v147
	s_nop 1
	v_cndmask_b32_e32 v153, v134, v36, vcc
	v_add_u32_e32 v36, 0xffffff62, v152
	v_cmp_le_i32_e32 vcc, v36, v147
	v_add_u32_e32 v36, 0xffffff43, v152
	s_nop 0
	v_cndmask_b32_e32 v52, v134, v52, vcc
	v_cmp_le_i32_e32 vcc, v36, v147
	v_add_u32_e32 v36, 0xffffff63, v152
	s_nop 0
	v_cndmask_b32_e32 v154, v134, v37, vcc
	v_cmp_le_i32_e32 vcc, v36, v147
	v_add_u32_e32 v36, 0xffffff48, v152
	v_exp_f32_e32 v37, v51
	v_cndmask_b32_e32 v53, v134, v53, vcc
	v_cmp_le_i32_e32 vcc, v36, v147
	v_add_u32_e32 v36, 0xffffff68, v152
	s_nop 0
	v_cndmask_b32_e32 v155, v134, v38, vcc
	v_cmp_le_i32_e32 vcc, v36, v147
	v_add_u32_e32 v36, 0xffffff49, v152
	v_exp_f32_e32 v38, v153
	v_cndmask_b32_e32 v54, v134, v54, vcc
	v_cmp_le_i32_e32 vcc, v36, v147
	v_add_u32_e32 v36, 0xffffff69, v152
	s_nop 0
	v_cndmask_b32_e32 v156, v134, v39, vcc
	v_cmp_le_i32_e32 vcc, v36, v147
	v_add_u32_e32 v36, 0xffffff4a, v152
	v_exp_f32_e32 v39, v154
	v_cndmask_b32_e32 v55, v134, v55, vcc
	v_cmp_le_i32_e32 vcc, v36, v147
	v_add_u32_e32 v36, 0xffffff6a, v152
	v_cvt_pk_bf16_f32 v154, v34, v35
	v_cndmask_b32_e32 v157, v134, v40, vcc
	v_cmp_le_i32_e32 vcc, v36, v147
	v_add_u32_e32 v36, 0xffffff4b, v152
	v_exp_f32_e32 v40, v52
	v_cndmask_b32_e32 v56, v134, v56, vcc
	v_cmp_le_i32_e32 vcc, v36, v147
	v_add_u32_e32 v36, 0xffffff6b, v152
	s_nop 0
	v_cndmask_b32_e32 v158, v134, v41, vcc
	v_cmp_le_i32_e32 vcc, v36, v147
	v_add_u32_e32 v36, 0xffffff50, v152
	v_exp_f32_e32 v41, v53
	v_cndmask_b32_e32 v57, v134, v57, vcc
	v_cmp_le_i32_e32 vcc, v36, v147
	v_add_u32_e32 v36, 0xffffff70, v152
	v_exp_f32_e32 v51, v57
	v_cndmask_b32_e32 v159, v134, v42, vcc
	v_cmp_le_i32_e32 vcc, v36, v147
	v_add_u32_e32 v36, 0xffffff51, v152
	v_exp_f32_e32 v52, v159
	v_cndmask_b32_e32 v58, v134, v58, vcc
	v_cmp_le_i32_e32 vcc, v36, v147
	v_add_u32_e32 v36, 0xffffff71, v152
	s_nop 0
	v_cndmask_b32_e32 v160, v134, v43, vcc
	v_cmp_le_i32_e32 vcc, v36, v147
	v_add_u32_e32 v36, 0xffffff52, v152
	v_pk_add_f32 v[42:43], v[34:35], 0 op_sel_hi:[1,0]
	v_cndmask_b32_e32 v59, v134, v59, vcc
	v_cmp_le_i32_e32 vcc, v36, v147
	v_add_u32_e32 v36, 0xffffff72, v152
	v_exp_f32_e32 v53, v160
	v_cndmask_b32_e32 v161, v134, v44, vcc
	v_cmp_le_i32_e32 vcc, v36, v147
	v_add_u32_e32 v36, 0xffffff53, v152
	v_exp_f32_e32 v44, v155
	v_cndmask_b32_e32 v60, v134, v60, vcc
	v_cmp_le_i32_e32 vcc, v36, v147
	v_add_u32_e32 v36, 0xffffff73, v152
	v_cvt_pk_bf16_f32 v155, v38, v39
	v_cndmask_b32_e32 v162, v134, v45, vcc
	v_cmp_le_i32_e32 vcc, v36, v147
	v_add_u32_e32 v36, 0xffffff58, v152
	v_exp_f32_e32 v45, v156
; __device__ __forceinline__ void pv(f32x16* o, int vb, bf16x8 pa0, bf16x8 pa1, bf16x8 pa2, bf16x8 pa3) {
; #pragma unroll
;     for (int d0 = 0; d0 < 2; ++d0) { s16x4 lo[4], hi[4];
; #pragma unroll
;         for (int ks = 0; ks < 4; ++ks) {
;             asm volatile("ds_read_b64_tr_b16 %0,%1 offset:%c2" : "=&v"(lo[ks]) : "v"(vb), "i"(d0 * 4096 + ks * 1024) : "memory");
;             asm volatile("ds_read_b64_tr_b16 %0,%1 offset:%c2" : "=&v"(hi[ks]) : "v"(vb), "i"(d0 * 4096 + ks * 1024 + 512) : "memory"); }
;         asm volatile("s_waitcnt lgkmcnt(0)" ::: "memory"); __builtin_amdgcn_sched_barrier(0);
;     ...
;         o[d0] = __builtin_amdgcn_mfma_f32_32x32x16_bf16(pa0, PK(0), o[d0], 0, 0, 0);
;         o[d0] = __builtin_amdgcn_mfma_f32_32x32x16_bf16(pa1, PK(1), o[d0], 0, 0, 0);
;         o[d0] = __builtin_amdgcn_mfma_f32_32x32x16_bf16(pa2, PK(2), o[d0], 0, 0, 0);
;         o[d0] = __builtin_amdgcn_mfma_f32_32x32x16_bf16(pa3, PK(3), o[d0], 0, 0, 0);
; template <bool BAND>
; __device__ __forceinline__ void tile_body(f32x16* o, float& l_reg, const bf16x8* qr, const LAS unsigned char* kbs, const LAS float* wb, int vb, float ci, int hi, int keybase, int qabs) {
;     ...
;         for (int r = 0; r < 16; ++r) { const int key = keybase + 8 * (r >> 2) + (r & 3); if (key > qabs) p0[r] = -INFINITY; if (key + 32 > qabs) p1[r] = -INFINITY; }
;     }
;     f32x2 s2 = {0.f, 0.f};
; #pragma unroll
;     for (int r = 0; r < 16; r += 2) {
;         p0[r] = __builtin_amdgcn_exp2f(p0[r]); p0[r + 1] = __builtin_amdgcn_exp2f(p0[r + 1]); p1[r] = __builtin_amdgcn_exp2f(p1[r]); p1[r + 1] = __builtin_amdgcn_exp2f(p1[r + 1]);
;         s2 += (f32x2){p0[r], p0[r + 1]}; s2 += (f32x2){p1[r], p1[r + 1]}; }
;     l_reg += s2.x + s2.y;
;     u32x4 pw0, pw1, pw2, pw3;
;     pw0 = (u32x4){cvtpk(p0[0], p0[1]), cvtpk(p0[2], p0[3]), cvtpk(p0[4], p0[5]), cvtpk(p0[6], p0[7])};
;     pw1 = (u32x4){cvtpk(p0[8], p0[9]), cvtpk(p0[10], p0[11]), cvtpk(p0[12], p0[13]), cvtpk(p0[14], p0[15])};
;     pw2 = (u32x4){cvtpk(p1[0], p1[1]), cvtpk(p1[2], p1[3]), cvtpk(p1[4], p1[5]), cvtpk(p1[6], p1[7])};
;     pw3 = (u32x4){cvtpk(p1[8], p1[9]), cvtpk(p1[10], p1[11]), cvtpk(p1[12], p1[13]), cvtpk(p1[14], p1[15])};
;     pv(o, vb, __builtin_bit_cast(bf16x8, pw0), __builtin_bit_cast(bf16x8, pw1), __builtin_bit_cast(bf16x8, pw2), __builtin_bit_cast(bf16x8, pw3));
	v_cndmask_b32_e32 v61, v134, v61, vcc
	v_cmp_le_i32_e32 vcc, v36, v147
	v_add_u32_e32 v36, 0xffffff78, v152
	v_exp_f32_e32 v57, v162
	v_cndmask_b32_e32 v163, v134, v46, vcc
	v_cmp_le_i32_e32 vcc, v36, v147
	v_add_u32_e32 v36, 0xffffff59, v152
	v_exp_f32_e32 v46, v54
	v_cndmask_b32_e32 v62, v134, v62, vcc
	v_cmp_le_i32_e32 vcc, v36, v147
	v_add_u32_e32 v36, 0xffffff79, v152
	v_exp_f32_e32 v54, v58
	v_cndmask_b32_e32 v164, v134, v47, vcc
	v_cmp_le_i32_e32 vcc, v36, v147
	v_add_u32_e32 v36, 0xffffff5a, v152
	v_exp_f32_e32 v47, v55
	v_cndmask_b32_e32 v63, v134, v63, vcc
	v_cmp_le_i32_e32 vcc, v36, v147
	v_add_u32_e32 v36, 0xffffff7a, v152
	v_exp_f32_e32 v55, v59
	v_cndmask_b32_e32 v165, v134, v48, vcc
	v_cmp_le_i32_e32 vcc, v36, v147
	v_add_u32_e32 v36, 0xffffff5b, v152
	v_exp_f32_e32 v48, v157
	v_cndmask_b32_e32 v166, v134, v64, vcc
	v_cmp_le_i32_e32 vcc, v36, v147
	v_add_u32_e32 v36, 0xffffff7b, v152
	v_exp_f32_e32 v58, v60
	v_cndmask_b32_e32 v167, v134, v49, vcc
	v_cmp_le_i32_e32 vcc, v36, v147
	v_exp_f32_e32 v36, v50
	v_exp_f32_e32 v49, v158
	v_exp_f32_e32 v50, v56
	v_exp_f32_e32 v56, v161
	v_pk_add_f32 v[42:43], v[36:37], v[42:43]
	v_exp_f32_e32 v59, v61
	v_pk_add_f32 v[42:43], v[38:39], v[42:43]
	v_exp_f32_e32 v64, v165
	v_pk_add_f32 v[42:43], v[40:41], v[42:43]
	v_cvt_pk_bf16_f32 v165, v50, v51
	v_pk_add_f32 v[42:43], v[44:45], v[42:43]
	v_exp_f32_e32 v60, v163
	v_pk_add_f32 v[42:43], v[46:47], v[42:43]
	v_exp_f32_e32 v61, v164
	v_pk_add_f32 v[42:43], v[48:49], v[42:43]
	v_cvt_pk_bf16_f32 v158, v52, v53
	v_pk_add_f32 v[42:43], v[50:51], v[42:43]
	ds_read_b64_tr_b16 v[50:51],v0 offset:0
	v_exp_f32_e32 v62, v62
	v_pk_add_f32 v[42:43], v[52:53], v[42:43]
	ds_read_b64_tr_b16 v[52:53],v0 offset:512
	v_exp_f32_e32 v63, v63
	v_pk_add_f32 v[42:43], v[54:55], v[42:43]
	v_exp_f32_e32 v170, v166
	v_cvt_pk_bf16_f32 v166, v54, v55
	ds_read_b64_tr_b16 v[54:55],v0 offset:1024
	v_cndmask_b32_e32 v152, v134, v65, vcc
	v_pk_add_f32 v[42:43], v[56:57], v[42:43]
	v_exp_f32_e32 v65, v167
	v_cvt_pk_bf16_f32 v159, v56, v57
	ds_read_b64_tr_b16 v[56:57],v0 offset:1536
	v_pk_add_f32 v[42:43], v[58:59], v[42:43]
	v_exp_f32_e32 v171, v152
	v_cvt_pk_bf16_f32 v167, v58, v59
	ds_read_b64_tr_b16 v[58:59],v0 offset:2048
	v_pk_add_f32 v[42:43], v[60:61], v[42:43]
	v_cvt_pk_bf16_f32 v160, v60, v61
	ds_read_b64_tr_b16 v[60:61],v0 offset:2560
	v_pk_add_f32 v[42:43], v[62:63], v[42:43]
	v_cvt_pk_bf16_f32 v168, v62, v63
	ds_read_b64_tr_b16 v[62:63],v0 offset:3072
	v_pk_add_f32 v[42:43], v[64:65], v[42:43]
	v_cvt_pk_bf16_f32 v161, v64, v65
	ds_read_b64_tr_b16 v[64:65],v0 offset:3584
	v_pk_add_f32 v[42:43], v[170:171], v[42:43]
	s_waitcnt lgkmcnt(0)
	v_cvt_pk_bf16_f32 v156, v44, v45
	v_add_f32_e32 v42, v42, v43
	v_add_f32_e32 v152, v148, v42
	v_cvt_pk_bf16_f32 v157, v48, v49
	v_cvt_pk_bf16_f32 v162, v36, v37
	v_cvt_pk_bf16_f32 v163, v40, v41
	v_cvt_pk_bf16_f32 v164, v46, v47
	v_cvt_pk_bf16_f32 v169, v170, v171
	v_mfma_f32_32x32x16_bf16 v[2:17], v[154:157], v[50:53], v[2:17]
	ds_read_b64_tr_b16 v[170:171],v0 offset:4096
	ds_read_b64_tr_b16 v[172:173],v0 offset:4608
	ds_read_b64_tr_b16 v[174:175],v0 offset:5120
	ds_read_b64_tr_b16 v[176:177],v0 offset:5632
	ds_read_b64_tr_b16 v[178:179],v0 offset:6144
	ds_read_b64_tr_b16 v[180:181],v0 offset:6656
	ds_read_b64_tr_b16 v[182:183],v0 offset:7168
	v_mfma_f32_32x32x16_bf16 v[2:17], v[158:161], v[54:57], v[2:17]
	ds_read_b64_tr_b16 v[184:185],v0 offset:7680
	s_nop 0
	v_mfma_f32_32x32x16_bf16 v[2:17], v[162:165], v[58:61], v[2:17]
	v_mfma_f32_32x32x16_bf16 v[2:17], v[166:169], v[62:65], v[2:17]
	s_waitcnt lgkmcnt(6)
	v_mfma_f32_32x32x16_bf16 v[18:33], v[154:157], v[170:173], v[18:33]
	s_mov_b64 s[68:69], 0
	s_waitcnt lgkmcnt(4)
	v_mfma_f32_32x32x16_bf16 v[18:33], v[158:161], v[174:177], v[18:33]
	s_waitcnt lgkmcnt(2)
	v_mfma_f32_32x32x16_bf16 v[18:33], v[162:165], v[178:181], v[18:33]
	s_waitcnt lgkmcnt(0)
	v_mfma_f32_32x32x16_bf16 v[18:33], v[166:169], v[182:185], v[18:33]
; #define LAS __attribute__((address_space(3)))
; __device__ __forceinline__ void pv(f32x16* o, int vb, bf16x8 pa0, bf16x8 pa1, bf16x8 pa2, bf16x8 pa3) {
; #pragma unroll
;     for (int d0 = 0; d0 < 2; ++d0) { s16x4 lo[4], hi[4];
; #pragma unroll
;         for (int ks = 0; ks < 4; ++ks) {
; template <bool BAND>
; __device__ __forceinline__ void tile_body(f32x16* o, float& l_reg, const bf16x8* qr, const LAS unsigned char* kbs, const LAS float* wb, int vb, float ci, int hi, int keybase, int qabs) {
;     f32x16 p0, p1;
; #pragma unroll
;     for (int g4 = 0; g4 < 4; ++g4) {
;         const f32x4 ba = *(const LAS f32x4*)(wb + 8 * g4 + 4 * hi) + ci, bb = *(const LAS f32x4*)(wb + 32 + 8 * g4 + 4 * hi) + ci;
; #pragma unroll
;         for (int e = 0; e < 4; ++e) { p0[4 * g4 + e] = ba[e]; p1[4 * g4 + e] = bb[e]; }
;     }
; #pragma unroll
;     for (int d0 = 0; d0 < 4; ++d0) {
;         const bf16x8 b0 = *(const LAS bf16x8*)(kbs + d0 * 2048), b1 = *(const LAS bf16x8*)(kbs + d0 * 2048 + 512);
;         p0 = __builtin_amdgcn_mfma_f32_32x32x16_bf16(b0, qr[d0], p0, 0, 0, 0); p1 = __builtin_amdgcn_mfma_f32_32x32x16_bf16(b1, qr[d0], p1, 0, 0, 0); }
;     if (BAND) {
; #pragma unroll
;         for (int r = 0; r < 16; ++r) { const int key = keybase + 8 * (r >> 2) + (r & 3); if (key > qabs) p0[r] = -INFINITY; if (key + 32 > qabs) p1[r] = -INFINITY; }
;     }
;     f32x2 s2 = {0.f, 0.f};
; #pragma unroll
;     for (int r = 0; r < 16; r += 2) {
;         p0[r] = __builtin_amdgcn_exp2f(p0[r]); p0[r + 1] = __builtin_amdgcn_exp2f(p0[r + 1]); p1[r] = __builtin_amdgcn_exp2f(p1[r]); p1[r + 1] = __builtin_amdgcn_exp2f(p1[r + 1]);
;         s2 += (f32x2){p0[r], p0[r + 1]}; s2 += (f32x2){p1[r], p1[r + 1]}; }
;     l_reg += s2.x + s2.y;
;     u32x4 pw0, pw1, pw2, pw3;
;     pw0 = (u32x4){cvtpk(p0[0], p0[1]), cvtpk(p0[2], p0[3]), cvtpk(p0[4], p0[5]), cvtpk(p0[6], p0[7])};
;     pw1 = (u32x4){cvtpk(p0[8], p0[9]), cvtpk(p0[10], p0[11]), cvtpk(p0[12], p0[13]), cvtpk(p0[14], p0[15])};
;     pw2 = (u32x4){cvtpk(p1[0], p1[1]), cvtpk(p1[2], p1[3]), cvtpk(p1[4], p1[5]), cvtpk(p1[6], p1[7])};
;     pw3 = (u32x4){cvtpk(p1[8], p1[9]), cvtpk(p1[10], p1[11]), cvtpk(p1[12], p1[13]), cvtpk(p1[14], p1[15])};
;     pv(o, vb, __builtin_bit_cast(bf16x8, pw0), __builtin_bit_cast(bf16x8, pw1), __builtin_bit_cast(bf16x8, pw2), __builtin_bit_cast(bf16x8, pw3));
.LBB0_823:
	s_andn2_b64 vcc, exec, s[68:69]
	s_cbranch_vccnz .Lmy_attjoin_C
	s_nop 4
	ds_read_b128 v[34:37], v150 offset:32768
	ds_read_b128 v[38:41], v150 offset:32800
	ds_read_b128 v[42:45], v150 offset:32832
	ds_read_b128 v[46:49], v150 offset:32864
	s_nop 0
	ds_read_b128 v[50:53], v150 offset:32896
	ds_read_b128 v[54:57], v150 offset:32928
	ds_read_b128 v[58:61], v150 offset:32960
	ds_read_b128 v[62:65], v150 offset:32992
	ds_read_b128 v[152:155], v149
	ds_read_b128 v[156:159], v149 offset:512
	s_waitcnt lgkmcnt(6)
	ds_read_b128 v[210:213], v149 offset:2048
	ds_read_b128 v[214:217], v149 offset:2560
	ds_read_b128 v[218:221], v149 offset:4096
	ds_read_b128 v[222:225], v149 offset:4608
	ds_read_b128 v[226:229], v149 offset:6144
	ds_read_b128 v[230:233], v149 offset:6656
	v_pk_add_f32 v[48:49], v[126:127], v[48:49]
	v_pk_add_f32 v[44:45], v[122:123], v[44:45]
	v_pk_add_f32 v[40:41], v[118:119], v[40:41]
	v_pk_add_f32 v[36:37], v[114:115], v[36:37]
	v_pk_add_f32 v[46:47], v[124:125], v[46:47]
	v_pk_add_f32 v[42:43], v[120:121], v[42:43]
	v_pk_add_f32 v[38:39], v[116:117], v[38:39]
	v_pk_add_f32 v[34:35], v[112:113], v[34:35]
	s_waitcnt lgkmcnt(8)
	v_pk_add_f32 v[64:65], v[126:127], v[64:65]
	v_pk_add_f32 v[60:61], v[122:123], v[60:61]
	s_waitcnt lgkmcnt(7)
	v_mfma_f32_32x32x16_bf16 v[34:49], v[152:155], v[94:97], v[34:49]
	v_add_f32_e64 v56, v118, v56
	v_add_f32_e64 v57, v119, v57
	v_add_f32_e64 v52, v114, v52
	v_add_f32_e64 v53, v115, v53
	v_add_f32_e64 v62, v124, v62
	v_add_f32_e64 v63, v125, v63
	v_pk_add_f32 v[58:59], v[120:121], v[58:59]
	v_pk_add_f32 v[54:55], v[116:117], v[54:55]
	v_pk_add_f32 v[50:51], v[112:113], v[50:51]
	s_waitcnt lgkmcnt(6)
	s_nop 0
	v_mfma_f32_32x32x16_bf16 v[50:65], v[156:159], v[94:97], v[50:65]
	s_waitcnt lgkmcnt(5)
	v_mfma_f32_32x32x16_bf16 v[34:49], v[210:213], v[98:101], v[34:49]
	s_waitcnt lgkmcnt(4)
	v_mfma_f32_32x32x16_bf16 v[50:65], v[214:217], v[98:101], v[50:65]
	s_waitcnt lgkmcnt(3)
	v_mfma_f32_32x32x16_bf16 v[34:49], v[218:221], v[102:105], v[34:49]
	s_waitcnt lgkmcnt(2)
	v_mfma_f32_32x32x16_bf16 v[50:65], v[222:225], v[102:105], v[50:65]
	s_waitcnt lgkmcnt(1)
	v_mfma_f32_32x32x16_bf16 v[34:49], v[226:229], v[90:93], v[34:49]
	s_waitcnt lgkmcnt(0)
	v_mfma_f32_32x32x16_bf16 v[50:65], v[230:233], v[90:93], v[50:65]
	s_nop 9
	v_exp_f32_e32 v34, v34
	v_exp_f32_e32 v35, v35
	v_exp_f32_e32 v36, v36
	v_exp_f32_e32 v37, v37
	v_exp_f32_e32 v38, v38
	v_pk_add_f32 v[152:153], v[34:35], 0 op_sel_hi:[1,0]
	v_exp_f32_e32 v39, v39
	v_exp_f32_e32 v50, v50
	v_exp_f32_e32 v51, v51
	v_exp_f32_e32 v52, v52
	v_exp_f32_e32 v53, v53
	v_exp_f32_e32 v54, v54
	v_pk_add_f32 v[152:153], v[50:51], v[152:153]
	v_exp_f32_e32 v55, v55
	v_pk_add_f32 v[152:153], v[36:37], v[152:153]
	v_exp_f32_e32 v40, v40
	v_exp_f32_e32 v41, v41
	v_pk_add_f32 v[152:153], v[52:53], v[152:153]
	v_exp_f32_e32 v56, v56
	v_exp_f32_e32 v57, v57
	v_pk_add_f32 v[152:153], v[38:39], v[152:153]
	v_exp_f32_e32 v42, v42
	v_exp_f32_e32 v43, v43
	v_pk_add_f32 v[152:153], v[54:55], v[152:153]
	v_exp_f32_e32 v58, v58
	v_exp_f32_e32 v59, v59
	v_pk_add_f32 v[152:153], v[40:41], v[152:153]
	v_exp_f32_e32 v44, v44
	v_exp_f32_e32 v45, v45
	v_pk_add_f32 v[152:153], v[56:57], v[152:153]
	v_exp_f32_e32 v60, v60
	v_exp_f32_e32 v61, v61
	v_pk_add_f32 v[152:153], v[42:43], v[152:153]
	v_exp_f32_e32 v46, v46
	v_exp_f32_e32 v47, v47
	v_cvt_pk_bf16_f32 v34, v34, v35
	v_cvt_pk_bf16_f32 v35, v36, v37
	v_cvt_pk_bf16_f32 v36, v38, v39
	v_cvt_pk_bf16_f32 v38, v42, v43
	v_cvt_pk_bf16_f32 v42, v50, v51
	ds_read_b64_tr_b16 v[50:51],v0 offset:0
	v_pk_add_f32 v[152:153], v[58:59], v[152:153]
	v_exp_f32_e32 v62, v62
	v_exp_f32_e32 v63, v63
	v_cvt_pk_bf16_f32 v43, v52, v53
	ds_read_b64_tr_b16 v[52:53],v0 offset:512
	v_pk_add_f32 v[152:153], v[44:45], v[152:153]
	v_exp_f32_e32 v48, v48
	v_exp_f32_e32 v49, v49
	v_cvt_pk_bf16_f32 v39, v44, v45
	v_cvt_pk_bf16_f32 v44, v54, v55
	ds_read_b64_tr_b16 v[54:55],v0 offset:1024
	v_pk_add_f32 v[152:153], v[60:61], v[152:153]
	v_exp_f32_e32 v64, v64
	v_exp_f32_e32 v65, v65
	v_cvt_pk_bf16_f32 v45, v56, v57
	ds_read_b64_tr_b16 v[56:57],v0 offset:1536
	v_pk_add_f32 v[152:153], v[46:47], v[152:153]
	v_cvt_pk_bf16_f32 v37, v40, v41
	v_cvt_pk_bf16_f32 v40, v46, v47
	v_cvt_pk_bf16_f32 v46, v58, v59
	ds_read_b64_tr_b16 v[58:59],v0 offset:2048
	v_pk_add_f32 v[152:153], v[62:63], v[152:153]
	v_cvt_pk_bf16_f32 v47, v60, v61
	ds_read_b64_tr_b16 v[60:61],v0 offset:2560
	v_pk_add_f32 v[152:153], v[48:49], v[152:153]
	v_cvt_pk_bf16_f32 v41, v48, v49
	v_cvt_pk_bf16_f32 v48, v62, v63
	ds_read_b64_tr_b16 v[62:63],v0 offset:3072
	v_pk_add_f32 v[152:153], v[64:65], v[152:153]
	v_cvt_pk_bf16_f32 v49, v64, v65
	ds_read_b64_tr_b16 v[64:65],v0 offset:3584
	s_waitcnt lgkmcnt(0)
	v_add_f32_e32 v149, v152, v153
	v_add_f32_e32 v152, v148, v149
	v_mfma_f32_32x32x16_bf16 v[2:17], v[34:37], v[50:53], v[2:17]
	ds_read_b64_tr_b16 v[50:51],v0 offset:4096
	ds_read_b64_tr_b16 v[52:53],v0 offset:4608
	v_mfma_f32_32x32x16_bf16 v[2:17], v[38:41], v[54:57], v[2:17]
	ds_read_b64_tr_b16 v[54:55],v0 offset:5120
	ds_read_b64_tr_b16 v[56:57],v0 offset:5632
	v_mfma_f32_32x32x16_bf16 v[2:17], v[42:45], v[58:61], v[2:17]
	ds_read_b64_tr_b16 v[58:59],v0 offset:6144
	ds_read_b64_tr_b16 v[60:61],v0 offset:6656
	ds_read_b64_tr_b16 v[154:155],v0 offset:7168
	ds_read_b64_tr_b16 v[156:157],v0 offset:7680
	s_nop 0
	v_mfma_f32_32x32x16_bf16 v[2:17], v[46:49], v[62:65], v[2:17]
	s_waitcnt lgkmcnt(6)
	v_mfma_f32_32x32x16_bf16 v[18:33], v[34:37], v[50:53], v[18:33]
	s_waitcnt lgkmcnt(4)
	v_mfma_f32_32x32x16_bf16 v[18:33], v[38:41], v[54:57], v[18:33]
	s_waitcnt lgkmcnt(2)
	v_mfma_f32_32x32x16_bf16 v[18:33], v[42:45], v[58:61], v[18:33]
	s_waitcnt lgkmcnt(0)
	v_mfma_f32_32x32x16_bf16 v[18:33], v[46:49], v[154:157], v[18:33]
	s_branch .Lmy_attjoin_C
